# v76 plus n128-shaped 16x16x32 hand tiles for MLP2A/MLP2B/OUT1 with 16-byte residual loads and stores via permlane16 swaps
# speedup vs baseline: 1.0244x; 1.0012x over previous
.Lt_mlp2bn:
	v_add_u32_e32 v169, s32, v164
	v_mfma_f32_16x16x32_f16 v[4:7], v[132:135], v[184:187], v[4:7]
	ds_read_b128 v[192:195], v169 offset:2064
	v_mfma_f32_16x16x32_f16 v[8:11], v[136:139], v[184:187], v[8:11]
	ds_read_b128 v[196:199], v169 offset:3088
	v_mfma_f32_16x16x32_f16 v[12:15], v[140:143], v[184:187], v[12:15]
	v_mfma_f32_16x16x32_f16 v[16:19], v[144:147], v[184:187], v[16:19]
	v_mfma_f32_16x16x32_f16 v[20:23], v[132:135], v[188:191], v[20:23]
	v_mfma_f32_16x16x32_f16 v[24:27], v[136:139], v[188:191], v[24:27]
	v_mfma_f32_16x16x32_f16 v[28:31], v[140:143], v[188:191], v[28:31]
	v_mfma_f32_16x16x32_f16 v[32:35], v[144:147], v[188:191], v[32:35]
	s_waitcnt vmcnt(6) lgkmcnt(0)
	s_barrier
	s_add_i32 s53, s32, 0x6000
	s_cmp_lg_u32 s32, 0x12000
	s_cselect_b32 s53, s53, 0
	v_add_u32_e32 v168, s53, v165
	v_add_u32_e32 v169, s53, v164
	v_mfma_f32_16x16x32_f16 v[36:39], v[132:135], v[192:195], v[36:39]
	ds_read_b128 v[148:151], v168 offset:16
	ds_read_b128 v[184:187], v169 offset:16
	v_mfma_f32_16x16x32_f16 v[40:43], v[136:139], v[192:195], v[40:43]
	ds_read_b128 v[152:155], v168 offset:1040
	ds_read_b128 v[188:191], v169 offset:1040
	v_mfma_f32_16x16x32_f16 v[44:47], v[140:143], v[192:195], v[44:47]
	ds_read_b128 v[156:159], v168 offset:2064
	v_mfma_f32_16x16x32_f16 v[48:51], v[144:147], v[192:195], v[48:51]
	ds_read_b128 v[160:163], v168 offset:3088
	v_mfma_f32_16x16x32_f16 v[52:55], v[132:135], v[196:199], v[52:55]
	s_add_u32 m0, s25, s32
	s_nop 0
	global_load_lds_dwordx4 v170, s[36:37]
	v_mfma_f32_16x16x32_f16 v[56:59], v[136:139], v[196:199], v[56:59]
	s_add_u32 m0, s25, s32
	s_add_u32 m0, m0, 0x400
	s_nop 0
	global_load_lds_dwordx4 v171, s[36:37]
	v_mfma_f32_16x16x32_f16 v[60:63], v[140:143], v[196:199], v[60:63]
	s_add_u32 m0, s31, s32
	s_nop 0
	global_load_lds_dwordx4 v170, s[98:99]
	v_mfma_f32_16x16x32_f16 v[64:67], v[144:147], v[196:199], v[64:67]
	s_waitcnt lgkmcnt(0)
	s_mov_b32 s32, s53
	s_add_u32 s36, s36, 64
	s_addc_u32 s37, s37, 0
	s_add_u32 s98, s98, 64
	s_addc_u32 s99, s99, 0
	v_add_u32_e32 v169, s32, v164
	v_mfma_f32_16x16x32_f16 v[4:7], v[148:151], v[184:187], v[4:7]
	ds_read_b128 v[192:195], v169 offset:2064
	v_mfma_f32_16x16x32_f16 v[8:11], v[152:155], v[184:187], v[8:11]
	ds_read_b128 v[196:199], v169 offset:3088
	v_mfma_f32_16x16x32_f16 v[12:15], v[156:159], v[184:187], v[12:15]
	v_mfma_f32_16x16x32_f16 v[16:19], v[160:163], v[184:187], v[16:19]
	v_mfma_f32_16x16x32_f16 v[20:23], v[148:151], v[188:191], v[20:23]
	v_mfma_f32_16x16x32_f16 v[24:27], v[152:155], v[188:191], v[24:27]
	v_mfma_f32_16x16x32_f16 v[28:31], v[156:159], v[188:191], v[28:31]
	v_mfma_f32_16x16x32_f16 v[32:35], v[160:163], v[188:191], v[32:35]
	s_waitcnt vmcnt(6) lgkmcnt(0)
	s_barrier
	s_add_i32 s53, s32, 0x6000
	s_cmp_lg_u32 s32, 0x12000
	s_cselect_b32 s53, s53, 0
	v_add_u32_e32 v168, s53, v165
	v_add_u32_e32 v169, s53, v164
	v_mfma_f32_16x16x32_f16 v[36:39], v[148:151], v[192:195], v[36:39]
	ds_read_b128 v[132:135], v168 offset:16
	ds_read_b128 v[184:187], v169 offset:16
	v_mfma_f32_16x16x32_f16 v[40:43], v[152:155], v[192:195], v[40:43]
	ds_read_b128 v[136:139], v168 offset:1040
	ds_read_b128 v[188:191], v169 offset:1040
	v_mfma_f32_16x16x32_f16 v[44:47], v[156:159], v[192:195], v[44:47]
	ds_read_b128 v[140:143], v168 offset:2064
	v_mfma_f32_16x16x32_f16 v[48:51], v[160:163], v[192:195], v[48:51]
	ds_read_b128 v[144:147], v168 offset:3088
	v_mfma_f32_16x16x32_f16 v[52:55], v[148:151], v[196:199], v[52:55]
	s_add_u32 m0, s25, s32
	s_nop 0
	global_load_lds_dwordx4 v170, s[36:37]
	v_mfma_f32_16x16x32_f16 v[56:59], v[152:155], v[196:199], v[56:59]
	s_add_u32 m0, s25, s32
	s_add_u32 m0, m0, 0x400
	s_nop 0
	global_load_lds_dwordx4 v171, s[36:37]
	v_mfma_f32_16x16x32_f16 v[60:63], v[156:159], v[196:199], v[60:63]
	s_add_u32 m0, s31, s32
	s_nop 0
	global_load_lds_dwordx4 v170, s[98:99]
	v_mfma_f32_16x16x32_f16 v[64:67], v[160:163], v[196:199], v[64:67]
	s_waitcnt lgkmcnt(0)
	s_mov_b32 s32, s53
	s_add_u32 s36, s36, 64
	s_addc_u32 s37, s37, 0
	s_add_u32 s98, s98, 64
	s_addc_u32 s99, s99, 0
	s_add_i32 s65, s65, 2
	s_cmp_lt_u32 s65, 124
	s_cbranch_scc1 .Lt_mlp2bn
	v_add_u32_e32 v169, s32, v164
	v_mfma_f32_16x16x32_f16 v[4:7], v[132:135], v[184:187], v[4:7]
	ds_read_b128 v[192:195], v169 offset:2064
	v_mfma_f32_16x16x32_f16 v[8:11], v[136:139], v[184:187], v[8:11]
	ds_read_b128 v[196:199], v169 offset:3088
	v_mfma_f32_16x16x32_f16 v[12:15], v[140:143], v[184:187], v[12:15]
	v_mfma_f32_16x16x32_f16 v[16:19], v[144:147], v[184:187], v[16:19]
	v_mfma_f32_16x16x32_f16 v[20:23], v[132:135], v[188:191], v[20:23]
	v_mfma_f32_16x16x32_f16 v[24:27], v[136:139], v[188:191], v[24:27]
	v_mfma_f32_16x16x32_f16 v[28:31], v[140:143], v[188:191], v[28:31]
	v_mfma_f32_16x16x32_f16 v[32:35], v[144:147], v[188:191], v[32:35]
	s_waitcnt vmcnt(6) lgkmcnt(0)
	s_barrier
	s_add_i32 s53, s32, 0x6000
	s_cmp_lg_u32 s32, 0x12000
	s_cselect_b32 s53, s53, 0
	v_add_u32_e32 v168, s53, v165
	v_add_u32_e32 v169, s53, v164
	v_mfma_f32_16x16x32_f16 v[36:39], v[132:135], v[192:195], v[36:39]
	ds_read_b128 v[148:151], v168 offset:16
	ds_read_b128 v[184:187], v169 offset:16
	v_mfma_f32_16x16x32_f16 v[40:43], v[136:139], v[192:195], v[40:43]
	ds_read_b128 v[152:155], v168 offset:1040
	ds_read_b128 v[188:191], v169 offset:1040
	v_mfma_f32_16x16x32_f16 v[44:47], v[140:143], v[192:195], v[44:47]
	ds_read_b128 v[156:159], v168 offset:2064
	v_mfma_f32_16x16x32_f16 v[48:51], v[144:147], v[192:195], v[48:51]
	ds_read_b128 v[160:163], v168 offset:3088
	v_mfma_f32_16x16x32_f16 v[52:55], v[132:135], v[196:199], v[52:55]
	v_mfma_f32_16x16x32_f16 v[56:59], v[136:139], v[196:199], v[56:59]
	v_mfma_f32_16x16x32_f16 v[60:63], v[140:143], v[196:199], v[60:63]
	v_mfma_f32_16x16x32_f16 v[64:67], v[144:147], v[196:199], v[64:67]
	s_waitcnt lgkmcnt(0)
	s_mov_b32 s32, s53
	v_add_u32_e32 v169, s32, v164
	v_mfma_f32_16x16x32_f16 v[4:7], v[148:151], v[184:187], v[4:7]
	ds_read_b128 v[192:195], v169 offset:2064
	v_mfma_f32_16x16x32_f16 v[8:11], v[152:155], v[184:187], v[8:11]
	ds_read_b128 v[196:199], v169 offset:3088
	v_mfma_f32_16x16x32_f16 v[12:15], v[156:159], v[184:187], v[12:15]
	v_mfma_f32_16x16x32_f16 v[16:19], v[160:163], v[184:187], v[16:19]
	v_mfma_f32_16x16x32_f16 v[20:23], v[148:151], v[188:191], v[20:23]
	v_mfma_f32_16x16x32_f16 v[24:27], v[152:155], v[188:191], v[24:27]
	v_mfma_f32_16x16x32_f16 v[28:31], v[156:159], v[188:191], v[28:31]
	v_mfma_f32_16x16x32_f16 v[32:35], v[160:163], v[188:191], v[32:35]
	s_waitcnt vmcnt(3) lgkmcnt(0)
	s_barrier
	s_add_i32 s53, s32, 0x6000
	s_cmp_lg_u32 s32, 0x12000
	s_cselect_b32 s53, s53, 0
	v_add_u32_e32 v168, s53, v165
	v_add_u32_e32 v169, s53, v164
	v_mfma_f32_16x16x32_f16 v[36:39], v[148:151], v[192:195], v[36:39]
	ds_read_b128 v[132:135], v168 offset:16
	ds_read_b128 v[184:187], v169 offset:16
	v_mfma_f32_16x16x32_f16 v[40:43], v[152:155], v[192:195], v[40:43]
	ds_read_b128 v[136:139], v168 offset:1040
	ds_read_b128 v[188:191], v169 offset:1040
	v_mfma_f32_16x16x32_f16 v[44:47], v[156:159], v[192:195], v[44:47]
	ds_read_b128 v[140:143], v168 offset:2064
	v_mfma_f32_16x16x32_f16 v[48:51], v[160:163], v[192:195], v[48:51]
	ds_read_b128 v[144:147], v168 offset:3088
	v_mfma_f32_16x16x32_f16 v[52:55], v[148:151], v[196:199], v[52:55]
	v_mfma_f32_16x16x32_f16 v[56:59], v[152:155], v[196:199], v[56:59]
	v_mfma_f32_16x16x32_f16 v[60:63], v[156:159], v[196:199], v[60:63]
	v_mfma_f32_16x16x32_f16 v[64:67], v[160:163], v[196:199], v[64:67]
	s_waitcnt lgkmcnt(0)
	s_mov_b32 s32, s53
	v_add_u32_e32 v169, s32, v164
	v_mfma_f32_16x16x32_f16 v[4:7], v[132:135], v[184:187], v[4:7]
	ds_read_b128 v[192:195], v169 offset:2064
	v_mfma_f32_16x16x32_f16 v[8:11], v[136:139], v[184:187], v[8:11]
	ds_read_b128 v[196:199], v169 offset:3088
	v_mfma_f32_16x16x32_f16 v[12:15], v[140:143], v[184:187], v[12:15]
	v_mfma_f32_16x16x32_f16 v[16:19], v[144:147], v[184:187], v[16:19]
	v_mfma_f32_16x16x32_f16 v[20:23], v[132:135], v[188:191], v[20:23]
	v_mfma_f32_16x16x32_f16 v[24:27], v[136:139], v[188:191], v[24:27]
	v_mfma_f32_16x16x32_f16 v[28:31], v[140:143], v[188:191], v[28:31]
	v_mfma_f32_16x16x32_f16 v[32:35], v[144:147], v[188:191], v[32:35]
	s_waitcnt vmcnt(0) lgkmcnt(0)
	s_barrier
	s_add_i32 s53, s32, 0x6000
	s_cmp_lg_u32 s32, 0x12000
	s_cselect_b32 s53, s53, 0
	v_add_u32_e32 v168, s53, v165
	v_add_u32_e32 v169, s53, v164
	v_mfma_f32_16x16x32_f16 v[36:39], v[132:135], v[192:195], v[36:39]
	ds_read_b128 v[148:151], v168 offset:16
	ds_read_b128 v[184:187], v169 offset:16
	v_mfma_f32_16x16x32_f16 v[40:43], v[136:139], v[192:195], v[40:43]
	ds_read_b128 v[152:155], v168 offset:1040
	ds_read_b128 v[188:191], v169 offset:1040
	v_mfma_f32_16x16x32_f16 v[44:47], v[140:143], v[192:195], v[44:47]
	ds_read_b128 v[156:159], v168 offset:2064
	v_mfma_f32_16x16x32_f16 v[48:51], v[144:147], v[192:195], v[48:51]
	ds_read_b128 v[160:163], v168 offset:3088
	v_mfma_f32_16x16x32_f16 v[52:55], v[132:135], v[196:199], v[52:55]
	v_mfma_f32_16x16x32_f16 v[56:59], v[136:139], v[196:199], v[56:59]
	v_mfma_f32_16x16x32_f16 v[60:63], v[140:143], v[196:199], v[60:63]
	v_mfma_f32_16x16x32_f16 v[64:67], v[144:147], v[196:199], v[64:67]
	s_waitcnt lgkmcnt(0)
	s_mov_b32 s32, s53
	v_add_u32_e32 v169, s32, v164
	v_mfma_f32_16x16x32_f16 v[4:7], v[148:151], v[184:187], v[4:7]
	ds_read_b128 v[192:195], v169 offset:2064
	v_mfma_f32_16x16x32_f16 v[8:11], v[152:155], v[184:187], v[8:11]
	ds_read_b128 v[196:199], v169 offset:3088
	v_mfma_f32_16x16x32_f16 v[12:15], v[156:159], v[184:187], v[12:15]
	v_mfma_f32_16x16x32_f16 v[16:19], v[160:163], v[184:187], v[16:19]
	v_mfma_f32_16x16x32_f16 v[20:23], v[148:151], v[188:191], v[20:23]
	v_mfma_f32_16x16x32_f16 v[24:27], v[152:155], v[188:191], v[24:27]
	v_mfma_f32_16x16x32_f16 v[28:31], v[156:159], v[188:191], v[28:31]
	v_mfma_f32_16x16x32_f16 v[32:35], v[160:163], v[188:191], v[32:35]
	s_waitcnt lgkmcnt(0)
	s_barrier
	v_mfma_f32_16x16x32_f16 v[36:39], v[148:151], v[192:195], v[36:39]
	v_mfma_f32_16x16x32_f16 v[40:43], v[152:155], v[192:195], v[40:43]
	v_mfma_f32_16x16x32_f16 v[44:47], v[156:159], v[192:195], v[44:47]
	v_mfma_f32_16x16x32_f16 v[48:51], v[160:163], v[192:195], v[48:51]
	v_mfma_f32_16x16x32_f16 v[52:55], v[148:151], v[196:199], v[52:55]
	v_mfma_f32_16x16x32_f16 v[56:59], v[152:155], v[196:199], v[56:59]
	v_mfma_f32_16x16x32_f16 v[60:63], v[156:159], v[196:199], v[60:63]
	v_mfma_f32_16x16x32_f16 v[64:67], v[160:163], v[196:199], v[64:67]
	s_sub_u32 s77, s30, 0x1000
	s_lshr_b32 s77, s77, 12
	s_add_u32 s77, s77, 1
	s_cmp_lt_u32 s30, 0x1000
	s_cselect_b32 s77, 0, s77
	s_mul_i32 s77, s77, 0x6000
	s_add_u32 s68, s46, s77
	s_addc_u32 s69, s47, 0
	s_add_u32 s68, s68, 0xfa2e600
	s_addc_u32 s69, s69, 0
	s_lshl_b32 s82, s30, 11
	s_add_u32 s80, s48, s82
	s_addc_u32 s81, s49, 0
	s_lshl_b32 s82, s28, 1
	s_add_u32 s80, s80, s82
	s_addc_u32 s81, s81, 0
	v_and_b32_e32 v172, 15, v200
	v_bfe_u32 v173, v200, 4, 2
	v_bfe_u32 v174, v200, 6, 1
	v_bfe_u32 v175, v200, 7, 2
	v_lshlrev_b32_e32 v176, 6, v174
	v_lshl_or_b32 v176, v173, 2, v176
	v_lshl_or_b32 v175, v175, 6, v172
	v_lshlrev_b32_e32 v175, 11, v175
	v_lshl_add_u32 v177, v176, 1, v175
	v_add_u32_e32 v176, s28, v176
	v_lshlrev_b32_e32 v176, 2, v176
	global_load_dwordx4 v[132:135], v176, s[68:69]
	global_load_dwordx4 v[136:139], v176, s[68:69] offset:64
	global_load_dwordx4 v[140:143], v176, s[68:69] offset:128
	global_load_dwordx4 v[144:147], v176, s[68:69] offset:192
	v_and_b32_e32 v172, 1, v173
	v_mul_u32_u24_e32 v172, 24, v172
	v_add_u32_e32 v177, v177, v172
	v_mov_b32_e32 v178, v177
	global_load_dwordx4 v[184:187], v178, s[80:81]
	global_load_dwordx4 v[188:191], v178, s[80:81] offset:64
	v_add_u32_e32 v178, 0x8000, v178
	global_load_dwordx4 v[192:195], v178, s[80:81]
	global_load_dwordx4 v[196:199], v178, s[80:81] offset:64
	s_waitcnt vmcnt(3)
	v_permlane16_swap_b32_e32 v184, v186
	v_permlane16_swap_b32_e32 v185, v187
	v_cvt_f32_f16_e32 v164, v184
	v_cvt_f32_f16_sdwa v165, v184 dst_sel:DWORD dst_unused:UNUSED_PAD src0_sel:WORD_1
	v_cvt_f32_f16_e32 v166, v185
	v_cvt_f32_f16_sdwa v167, v185 dst_sel:DWORD dst_unused:UNUSED_PAD src0_sel:WORD_1
	v_pk_mul_f32 v[164:165], v[164:165], s[84:85] op_sel_hi:[1,0]
	v_pk_mul_f32 v[166:167], v[166:167], s[84:85] op_sel_hi:[1,0]
	v_pk_fma_f32 v[4:5], v[4:5], v[132:133], v[164:165]
	v_pk_fma_f32 v[6:7], v[6:7], v[134:135], v[166:167]
	v_cvt_pk_f16_f32 v172, v4, v5
	v_cvt_pk_f16_f32 v173, v6, v7
	v_cvt_f32_f16_e32 v164, v186
	v_cvt_f32_f16_sdwa v165, v186 dst_sel:DWORD dst_unused:UNUSED_PAD src0_sel:WORD_1
	v_cvt_f32_f16_e32 v166, v187
	v_cvt_f32_f16_sdwa v167, v187 dst_sel:DWORD dst_unused:UNUSED_PAD src0_sel:WORD_1
	v_pk_mul_f32 v[164:165], v[164:165], s[84:85] op_sel_hi:[1,0]
	v_pk_mul_f32 v[166:167], v[166:167], s[84:85] op_sel_hi:[1,0]
	v_pk_fma_f32 v[8:9], v[8:9], v[136:137], v[164:165]
	v_pk_fma_f32 v[10:11], v[10:11], v[138:139], v[166:167]
	v_cvt_pk_f16_f32 v174, v8, v9
	v_cvt_pk_f16_f32 v175, v10, v11
	s_nop 1
	v_permlane16_swap_b32_e32 v172, v174
	v_permlane16_swap_b32_e32 v173, v175
	global_store_dwordx4 v177, v[172:175], s[80:81]
	s_waitcnt vmcnt(3)
	v_permlane16_swap_b32_e32 v188, v190
	v_permlane16_swap_b32_e32 v189, v191
	v_cvt_f32_f16_e32 v164, v188
	v_cvt_f32_f16_sdwa v165, v188 dst_sel:DWORD dst_unused:UNUSED_PAD src0_sel:WORD_1
	v_cvt_f32_f16_e32 v166, v189
	v_cvt_f32_f16_sdwa v167, v189 dst_sel:DWORD dst_unused:UNUSED_PAD src0_sel:WORD_1
	v_pk_mul_f32 v[164:165], v[164:165], s[84:85] op_sel_hi:[1,0]
	v_pk_mul_f32 v[166:167], v[166:167], s[84:85] op_sel_hi:[1,0]
	v_pk_fma_f32 v[12:13], v[12:13], v[140:141], v[164:165]
	v_pk_fma_f32 v[14:15], v[14:15], v[142:143], v[166:167]
	v_cvt_pk_f16_f32 v228, v12, v13
	v_cvt_pk_f16_f32 v229, v14, v15
	v_cvt_f32_f16_e32 v164, v190
	v_cvt_f32_f16_sdwa v165, v190 dst_sel:DWORD dst_unused:UNUSED_PAD src0_sel:WORD_1
	v_cvt_f32_f16_e32 v166, v191
	v_cvt_f32_f16_sdwa v167, v191 dst_sel:DWORD dst_unused:UNUSED_PAD src0_sel:WORD_1
	v_pk_mul_f32 v[164:165], v[164:165], s[84:85] op_sel_hi:[1,0]
	v_pk_mul_f32 v[166:167], v[166:167], s[84:85] op_sel_hi:[1,0]
	v_pk_fma_f32 v[16:17], v[16:17], v[144:145], v[164:165]
	v_pk_fma_f32 v[18:19], v[18:19], v[146:147], v[166:167]
	v_cvt_pk_f16_f32 v230, v16, v17
	v_cvt_pk_f16_f32 v231, v18, v19
	s_nop 1
	v_permlane16_swap_b32_e32 v228, v230
	v_permlane16_swap_b32_e32 v229, v231
	global_store_dwordx4 v177, v[228:231], s[80:81] offset:64
	v_add_u32_e32 v177, 0x8000, v177
	v_add_u32_e32 v178, 0x8000, v178
	global_load_dwordx4 v[184:187], v178, s[80:81]
	global_load_dwordx4 v[188:191], v178, s[80:81] offset:64
	s_waitcnt vmcnt(5)
	v_permlane16_swap_b32_e32 v192, v194
	v_permlane16_swap_b32_e32 v193, v195
	v_cvt_f32_f16_e32 v164, v192
	v_cvt_f32_f16_sdwa v165, v192 dst_sel:DWORD dst_unused:UNUSED_PAD src0_sel:WORD_1
	v_cvt_f32_f16_e32 v166, v193
	v_cvt_f32_f16_sdwa v167, v193 dst_sel:DWORD dst_unused:UNUSED_PAD src0_sel:WORD_1
	v_pk_mul_f32 v[164:165], v[164:165], s[84:85] op_sel_hi:[1,0]
	v_pk_mul_f32 v[166:167], v[166:167], s[84:85] op_sel_hi:[1,0]
	v_pk_fma_f32 v[20:21], v[20:21], v[132:133], v[164:165]
	v_pk_fma_f32 v[22:23], v[22:23], v[134:135], v[166:167]
	v_cvt_pk_f16_f32 v172, v20, v21
	v_cvt_pk_f16_f32 v173, v22, v23
	v_cvt_f32_f16_e32 v164, v194
	v_cvt_f32_f16_sdwa v165, v194 dst_sel:DWORD dst_unused:UNUSED_PAD src0_sel:WORD_1
	v_cvt_f32_f16_e32 v166, v195
	v_cvt_f32_f16_sdwa v167, v195 dst_sel:DWORD dst_unused:UNUSED_PAD src0_sel:WORD_1
	v_pk_mul_f32 v[164:165], v[164:165], s[84:85] op_sel_hi:[1,0]
	v_pk_mul_f32 v[166:167], v[166:167], s[84:85] op_sel_hi:[1,0]
	v_pk_fma_f32 v[24:25], v[24:25], v[136:137], v[164:165]
	v_pk_fma_f32 v[26:27], v[26:27], v[138:139], v[166:167]
	v_cvt_pk_f16_f32 v174, v24, v25
	v_cvt_pk_f16_f32 v175, v26, v27
	s_nop 1
	v_permlane16_swap_b32_e32 v172, v174
	v_permlane16_swap_b32_e32 v173, v175
	global_store_dwordx4 v177, v[172:175], s[80:81]
	s_waitcnt vmcnt(5)
	v_permlane16_swap_b32_e32 v196, v198
	v_permlane16_swap_b32_e32 v197, v199
	v_cvt_f32_f16_e32 v164, v196
	v_cvt_f32_f16_sdwa v165, v196 dst_sel:DWORD dst_unused:UNUSED_PAD src0_sel:WORD_1
	v_cvt_f32_f16_e32 v166, v197
	v_cvt_f32_f16_sdwa v167, v197 dst_sel:DWORD dst_unused:UNUSED_PAD src0_sel:WORD_1
	v_pk_mul_f32 v[164:165], v[164:165], s[84:85] op_sel_hi:[1,0]
	v_pk_mul_f32 v[166:167], v[166:167], s[84:85] op_sel_hi:[1,0]
	v_pk_fma_f32 v[28:29], v[28:29], v[140:141], v[164:165]
	v_pk_fma_f32 v[30:31], v[30:31], v[142:143], v[166:167]
	v_cvt_pk_f16_f32 v228, v28, v29
	v_cvt_pk_f16_f32 v229, v30, v31
	v_cvt_f32_f16_e32 v164, v198
	v_cvt_f32_f16_sdwa v165, v198 dst_sel:DWORD dst_unused:UNUSED_PAD src0_sel:WORD_1
	v_cvt_f32_f16_e32 v166, v199
	v_cvt_f32_f16_sdwa v167, v199 dst_sel:DWORD dst_unused:UNUSED_PAD src0_sel:WORD_1
	v_pk_mul_f32 v[164:165], v[164:165], s[84:85] op_sel_hi:[1,0]
	v_pk_mul_f32 v[166:167], v[166:167], s[84:85] op_sel_hi:[1,0]
	v_pk_fma_f32 v[32:33], v[32:33], v[144:145], v[164:165]
	v_pk_fma_f32 v[34:35], v[34:35], v[146:147], v[166:167]
	v_cvt_pk_f16_f32 v230, v32, v33
	v_cvt_pk_f16_f32 v231, v34, v35
	s_nop 1
	v_permlane16_swap_b32_e32 v228, v230
	v_permlane16_swap_b32_e32 v229, v231
	global_store_dwordx4 v177, v[228:231], s[80:81] offset:64
	v_add_u32_e32 v177, 0x8000, v177
	v_add_u32_e32 v178, 0x8000, v178
	global_load_dwordx4 v[192:195], v178, s[80:81]
	global_load_dwordx4 v[196:199], v178, s[80:81] offset:64
	s_waitcnt vmcnt(5)
	v_permlane16_swap_b32_e32 v184, v186
	v_permlane16_swap_b32_e32 v185, v187
	v_cvt_f32_f16_e32 v164, v184
	v_cvt_f32_f16_sdwa v165, v184 dst_sel:DWORD dst_unused:UNUSED_PAD src0_sel:WORD_1
	v_cvt_f32_f16_e32 v166, v185
	v_cvt_f32_f16_sdwa v167, v185 dst_sel:DWORD dst_unused:UNUSED_PAD src0_sel:WORD_1
	v_pk_mul_f32 v[164:165], v[164:165], s[84:85] op_sel_hi:[1,0]
	v_pk_mul_f32 v[166:167], v[166:167], s[84:85] op_sel_hi:[1,0]
	v_pk_fma_f32 v[36:37], v[36:37], v[132:133], v[164:165]
	v_pk_fma_f32 v[38:39], v[38:39], v[134:135], v[166:167]
	v_cvt_pk_f16_f32 v172, v36, v37
	v_cvt_pk_f16_f32 v173, v38, v39
	v_cvt_f32_f16_e32 v164, v186
	v_cvt_f32_f16_sdwa v165, v186 dst_sel:DWORD dst_unused:UNUSED_PAD src0_sel:WORD_1
	v_cvt_f32_f16_e32 v166, v187
	v_cvt_f32_f16_sdwa v167, v187 dst_sel:DWORD dst_unused:UNUSED_PAD src0_sel:WORD_1
	v_pk_mul_f32 v[164:165], v[164:165], s[84:85] op_sel_hi:[1,0]
	v_pk_mul_f32 v[166:167], v[166:167], s[84:85] op_sel_hi:[1,0]
	v_pk_fma_f32 v[40:41], v[40:41], v[136:137], v[164:165]
	v_pk_fma_f32 v[42:43], v[42:43], v[138:139], v[166:167]
	v_cvt_pk_f16_f32 v174, v40, v41
	v_cvt_pk_f16_f32 v175, v42, v43
	s_nop 1
	v_permlane16_swap_b32_e32 v172, v174
	v_permlane16_swap_b32_e32 v173, v175
	global_store_dwordx4 v177, v[172:175], s[80:81]
	s_waitcnt vmcnt(5)
	v_permlane16_swap_b32_e32 v188, v190
	v_permlane16_swap_b32_e32 v189, v191
	v_cvt_f32_f16_e32 v164, v188
	v_cvt_f32_f16_sdwa v165, v188 dst_sel:DWORD dst_unused:UNUSED_PAD src0_sel:WORD_1
	v_cvt_f32_f16_e32 v166, v189
	v_cvt_f32_f16_sdwa v167, v189 dst_sel:DWORD dst_unused:UNUSED_PAD src0_sel:WORD_1
	v_pk_mul_f32 v[164:165], v[164:165], s[84:85] op_sel_hi:[1,0]
	v_pk_mul_f32 v[166:167], v[166:167], s[84:85] op_sel_hi:[1,0]
	v_pk_fma_f32 v[44:45], v[44:45], v[140:141], v[164:165]
	v_pk_fma_f32 v[46:47], v[46:47], v[142:143], v[166:167]
	v_cvt_pk_f16_f32 v228, v44, v45
	v_cvt_pk_f16_f32 v229, v46, v47
	v_cvt_f32_f16_e32 v164, v190
	v_cvt_f32_f16_sdwa v165, v190 dst_sel:DWORD dst_unused:UNUSED_PAD src0_sel:WORD_1
	v_cvt_f32_f16_e32 v166, v191
	v_cvt_f32_f16_sdwa v167, v191 dst_sel:DWORD dst_unused:UNUSED_PAD src0_sel:WORD_1
	v_pk_mul_f32 v[164:165], v[164:165], s[84:85] op_sel_hi:[1,0]
	v_pk_mul_f32 v[166:167], v[166:167], s[84:85] op_sel_hi:[1,0]
	v_pk_fma_f32 v[48:49], v[48:49], v[144:145], v[164:165]
	v_pk_fma_f32 v[50:51], v[50:51], v[146:147], v[166:167]
	v_cvt_pk_f16_f32 v230, v48, v49
	v_cvt_pk_f16_f32 v231, v50, v51
	s_nop 1
	v_permlane16_swap_b32_e32 v228, v230
	v_permlane16_swap_b32_e32 v229, v231
	global_store_dwordx4 v177, v[228:231], s[80:81] offset:64
	v_add_u32_e32 v177, 0x8000, v177
	s_waitcnt vmcnt(3)
	v_permlane16_swap_b32_e32 v192, v194
	v_permlane16_swap_b32_e32 v193, v195
	v_cvt_f32_f16_e32 v164, v192
	v_cvt_f32_f16_sdwa v165, v192 dst_sel:DWORD dst_unused:UNUSED_PAD src0_sel:WORD_1
	v_cvt_f32_f16_e32 v166, v193
	v_cvt_f32_f16_sdwa v167, v193 dst_sel:DWORD dst_unused:UNUSED_PAD src0_sel:WORD_1
	v_pk_mul_f32 v[164:165], v[164:165], s[84:85] op_sel_hi:[1,0]
	v_pk_mul_f32 v[166:167], v[166:167], s[84:85] op_sel_hi:[1,0]
	v_pk_fma_f32 v[52:53], v[52:53], v[132:133], v[164:165]
	v_pk_fma_f32 v[54:55], v[54:55], v[134:135], v[166:167]
	v_cvt_pk_f16_f32 v172, v52, v53
	v_cvt_pk_f16_f32 v173, v54, v55
	v_cvt_f32_f16_e32 v164, v194
	v_cvt_f32_f16_sdwa v165, v194 dst_sel:DWORD dst_unused:UNUSED_PAD src0_sel:WORD_1
	v_cvt_f32_f16_e32 v166, v195
	v_cvt_f32_f16_sdwa v167, v195 dst_sel:DWORD dst_unused:UNUSED_PAD src0_sel:WORD_1
	v_pk_mul_f32 v[164:165], v[164:165], s[84:85] op_sel_hi:[1,0]
	v_pk_mul_f32 v[166:167], v[166:167], s[84:85] op_sel_hi:[1,0]
	v_pk_fma_f32 v[56:57], v[56:57], v[136:137], v[164:165]
	v_pk_fma_f32 v[58:59], v[58:59], v[138:139], v[166:167]
	v_cvt_pk_f16_f32 v174, v56, v57
	v_cvt_pk_f16_f32 v175, v58, v59
	s_nop 1
	v_permlane16_swap_b32_e32 v172, v174
	v_permlane16_swap_b32_e32 v173, v175
	global_store_dwordx4 v177, v[172:175], s[80:81]
	s_waitcnt vmcnt(3)
	v_permlane16_swap_b32_e32 v196, v198
	v_permlane16_swap_b32_e32 v197, v199
	v_cvt_f32_f16_e32 v164, v196
	v_cvt_f32_f16_sdwa v165, v196 dst_sel:DWORD dst_unused:UNUSED_PAD src0_sel:WORD_1
	v_cvt_f32_f16_e32 v166, v197
	v_cvt_f32_f16_sdwa v167, v197 dst_sel:DWORD dst_unused:UNUSED_PAD src0_sel:WORD_1
	v_pk_mul_f32 v[164:165], v[164:165], s[84:85] op_sel_hi:[1,0]
	v_pk_mul_f32 v[166:167], v[166:167], s[84:85] op_sel_hi:[1,0]
	v_pk_fma_f32 v[60:61], v[60:61], v[140:141], v[164:165]
	v_pk_fma_f32 v[62:63], v[62:63], v[142:143], v[166:167]
	v_cvt_pk_f16_f32 v228, v60, v61
	v_cvt_pk_f16_f32 v229, v62, v63
	v_cvt_f32_f16_e32 v164, v198
	v_cvt_f32_f16_sdwa v165, v198 dst_sel:DWORD dst_unused:UNUSED_PAD src0_sel:WORD_1
	v_cvt_f32_f16_e32 v166, v199
	v_cvt_f32_f16_sdwa v167, v199 dst_sel:DWORD dst_unused:UNUSED_PAD src0_sel:WORD_1
	v_pk_mul_f32 v[164:165], v[164:165], s[84:85] op_sel_hi:[1,0]
	v_pk_mul_f32 v[166:167], v[166:167], s[84:85] op_sel_hi:[1,0]
	v_pk_fma_f32 v[64:65], v[64:65], v[144:145], v[164:165]
	v_pk_fma_f32 v[66:67], v[66:67], v[146:147], v[166:167]
	v_cvt_pk_f16_f32 v230, v64, v65
	v_cvt_pk_f16_f32 v231, v66, v67
	s_nop 1
	v_permlane16_swap_b32_e32 v228, v230
	v_permlane16_swap_b32_e32 v229, v231
	global_store_dwordx4 v177, v[228:231], s[80:81] offset:64
	s_nop 1
	s_add_i32 s24, s24, s64
	s_cmpk_gt_i32 s24, 0x27f
	s_cbranch_scc1 .LBB0_67
	s_branch .LBB0_51

.Lt_out1n:
	v_add_u32_e32 v169, s52, v164
	v_mfma_f32_16x16x32_f16 v[4:7], v[132:135], v[184:187], v[4:7]
	ds_read_b128 v[192:195], v169 offset:2064
	v_mfma_f32_16x16x32_f16 v[8:11], v[136:139], v[184:187], v[8:11]
	ds_read_b128 v[196:199], v169 offset:3088
	v_mfma_f32_16x16x32_f16 v[12:15], v[140:143], v[184:187], v[12:15]
	v_mfma_f32_16x16x32_f16 v[16:19], v[144:147], v[184:187], v[16:19]
	v_mfma_f32_16x16x32_f16 v[20:23], v[132:135], v[188:191], v[20:23]
	v_mfma_f32_16x16x32_f16 v[24:27], v[136:139], v[188:191], v[24:27]
	v_mfma_f32_16x16x32_f16 v[28:31], v[140:143], v[188:191], v[28:31]
	v_mfma_f32_16x16x32_f16 v[32:35], v[144:147], v[188:191], v[32:35]
	s_waitcnt vmcnt(6) lgkmcnt(0)
	s_barrier
	s_add_i32 s53, s52, 0x6000
	s_cmp_lg_u32 s52, 0x12000
	s_cselect_b32 s53, s53, 0
	v_add_u32_e32 v168, s53, v165
	v_add_u32_e32 v169, s53, v164
	v_mfma_f32_16x16x32_f16 v[36:39], v[132:135], v[192:195], v[36:39]
	ds_read_b128 v[148:151], v168 offset:16
	ds_read_b128 v[184:187], v169 offset:16
	v_mfma_f32_16x16x32_f16 v[40:43], v[136:139], v[192:195], v[40:43]
	ds_read_b128 v[152:155], v168 offset:1040
	ds_read_b128 v[188:191], v169 offset:1040
	v_mfma_f32_16x16x32_f16 v[44:47], v[140:143], v[192:195], v[44:47]
	ds_read_b128 v[156:159], v168 offset:2064
	v_mfma_f32_16x16x32_f16 v[48:51], v[144:147], v[192:195], v[48:51]
	ds_read_b128 v[160:163], v168 offset:3088
	v_mfma_f32_16x16x32_f16 v[52:55], v[132:135], v[196:199], v[52:55]
	s_add_u32 m0, s31, s52
	s_nop 0
	global_load_lds_dwordx4 v170, s[34:35]
	v_mfma_f32_16x16x32_f16 v[56:59], v[136:139], v[196:199], v[56:59]
	s_add_u32 m0, s31, s52
	s_add_u32 m0, m0, 0x400
	s_nop 0
	global_load_lds_dwordx4 v171, s[34:35]
	v_mfma_f32_16x16x32_f16 v[60:63], v[140:143], v[196:199], v[60:63]
	s_add_u32 m0, s32, s52
	s_nop 0
	global_load_lds_dwordx4 v170, s[36:37]
	v_mfma_f32_16x16x32_f16 v[64:67], v[144:147], v[196:199], v[64:67]
	s_waitcnt lgkmcnt(0)
	s_mov_b32 s52, s53
	s_add_u32 s34, s34, 64
	s_addc_u32 s35, s35, 0
	s_add_u32 s36, s36, 64
	s_addc_u32 s37, s37, 0
	v_add_u32_e32 v169, s52, v164
	v_mfma_f32_16x16x32_f16 v[4:7], v[148:151], v[184:187], v[4:7]
	ds_read_b128 v[192:195], v169 offset:2064
	v_mfma_f32_16x16x32_f16 v[8:11], v[152:155], v[184:187], v[8:11]
	ds_read_b128 v[196:199], v169 offset:3088
	v_mfma_f32_16x16x32_f16 v[12:15], v[156:159], v[184:187], v[12:15]
	v_mfma_f32_16x16x32_f16 v[16:19], v[160:163], v[184:187], v[16:19]
	v_mfma_f32_16x16x32_f16 v[20:23], v[148:151], v[188:191], v[20:23]
	v_mfma_f32_16x16x32_f16 v[24:27], v[152:155], v[188:191], v[24:27]
	v_mfma_f32_16x16x32_f16 v[28:31], v[156:159], v[188:191], v[28:31]
	v_mfma_f32_16x16x32_f16 v[32:35], v[160:163], v[188:191], v[32:35]
	s_waitcnt vmcnt(6) lgkmcnt(0)
	s_barrier
	s_add_i32 s53, s52, 0x6000
	s_cmp_lg_u32 s52, 0x12000
	s_cselect_b32 s53, s53, 0
	v_add_u32_e32 v168, s53, v165
	v_add_u32_e32 v169, s53, v164
	v_mfma_f32_16x16x32_f16 v[36:39], v[148:151], v[192:195], v[36:39]
	ds_read_b128 v[132:135], v168 offset:16
	ds_read_b128 v[184:187], v169 offset:16
	v_mfma_f32_16x16x32_f16 v[40:43], v[152:155], v[192:195], v[40:43]
	ds_read_b128 v[136:139], v168 offset:1040
	ds_read_b128 v[188:191], v169 offset:1040
	v_mfma_f32_16x16x32_f16 v[44:47], v[156:159], v[192:195], v[44:47]
	ds_read_b128 v[140:143], v168 offset:2064
	v_mfma_f32_16x16x32_f16 v[48:51], v[160:163], v[192:195], v[48:51]
	ds_read_b128 v[144:147], v168 offset:3088
	v_mfma_f32_16x16x32_f16 v[52:55], v[148:151], v[196:199], v[52:55]
	s_add_u32 m0, s31, s52
	s_nop 0
	global_load_lds_dwordx4 v170, s[34:35]
	v_mfma_f32_16x16x32_f16 v[56:59], v[152:155], v[196:199], v[56:59]
	s_add_u32 m0, s31, s52
	s_add_u32 m0, m0, 0x400
	s_nop 0
	global_load_lds_dwordx4 v171, s[34:35]
	v_mfma_f32_16x16x32_f16 v[60:63], v[156:159], v[196:199], v[60:63]
	s_add_u32 m0, s32, s52
	s_nop 0
	global_load_lds_dwordx4 v170, s[36:37]
	v_mfma_f32_16x16x32_f16 v[64:67], v[160:163], v[196:199], v[64:67]
	s_waitcnt lgkmcnt(0)
	s_mov_b32 s52, s53
	s_add_u32 s34, s34, 64
	s_addc_u32 s35, s35, 0
	s_add_u32 s36, s36, 64
	s_addc_u32 s37, s37, 0
	s_add_i32 s54, s54, 2
	s_cmp_lt_u32 s54, 28
	s_cbranch_scc1 .Lt_out1n
	v_add_u32_e32 v169, s52, v164
	v_mfma_f32_16x16x32_f16 v[4:7], v[132:135], v[184:187], v[4:7]
	ds_read_b128 v[192:195], v169 offset:2064
	v_mfma_f32_16x16x32_f16 v[8:11], v[136:139], v[184:187], v[8:11]
	ds_read_b128 v[196:199], v169 offset:3088
	v_mfma_f32_16x16x32_f16 v[12:15], v[140:143], v[184:187], v[12:15]
	v_mfma_f32_16x16x32_f16 v[16:19], v[144:147], v[184:187], v[16:19]
	v_mfma_f32_16x16x32_f16 v[20:23], v[132:135], v[188:191], v[20:23]
	v_mfma_f32_16x16x32_f16 v[24:27], v[136:139], v[188:191], v[24:27]
	v_mfma_f32_16x16x32_f16 v[28:31], v[140:143], v[188:191], v[28:31]
	v_mfma_f32_16x16x32_f16 v[32:35], v[144:147], v[188:191], v[32:35]
	s_waitcnt vmcnt(6) lgkmcnt(0)
	s_barrier
	s_add_i32 s53, s52, 0x6000
	s_cmp_lg_u32 s52, 0x12000
	s_cselect_b32 s53, s53, 0
	v_add_u32_e32 v168, s53, v165
	v_add_u32_e32 v169, s53, v164
	v_mfma_f32_16x16x32_f16 v[36:39], v[132:135], v[192:195], v[36:39]
	ds_read_b128 v[148:151], v168 offset:16
	ds_read_b128 v[184:187], v169 offset:16
	v_mfma_f32_16x16x32_f16 v[40:43], v[136:139], v[192:195], v[40:43]
	ds_read_b128 v[152:155], v168 offset:1040
	ds_read_b128 v[188:191], v169 offset:1040
	v_mfma_f32_16x16x32_f16 v[44:47], v[140:143], v[192:195], v[44:47]
	ds_read_b128 v[156:159], v168 offset:2064
	v_mfma_f32_16x16x32_f16 v[48:51], v[144:147], v[192:195], v[48:51]
	ds_read_b128 v[160:163], v168 offset:3088
	v_mfma_f32_16x16x32_f16 v[52:55], v[132:135], v[196:199], v[52:55]
	v_mfma_f32_16x16x32_f16 v[56:59], v[136:139], v[196:199], v[56:59]
	v_mfma_f32_16x16x32_f16 v[60:63], v[140:143], v[196:199], v[60:63]
	v_mfma_f32_16x16x32_f16 v[64:67], v[144:147], v[196:199], v[64:67]
	s_waitcnt lgkmcnt(0)
	s_mov_b32 s52, s53
	v_add_u32_e32 v169, s52, v164
	v_mfma_f32_16x16x32_f16 v[4:7], v[148:151], v[184:187], v[4:7]
	ds_read_b128 v[192:195], v169 offset:2064
	v_mfma_f32_16x16x32_f16 v[8:11], v[152:155], v[184:187], v[8:11]
	ds_read_b128 v[196:199], v169 offset:3088
	v_mfma_f32_16x16x32_f16 v[12:15], v[156:159], v[184:187], v[12:15]
	v_mfma_f32_16x16x32_f16 v[16:19], v[160:163], v[184:187], v[16:19]
	v_mfma_f32_16x16x32_f16 v[20:23], v[148:151], v[188:191], v[20:23]
	v_mfma_f32_16x16x32_f16 v[24:27], v[152:155], v[188:191], v[24:27]
	v_mfma_f32_16x16x32_f16 v[28:31], v[156:159], v[188:191], v[28:31]
	v_mfma_f32_16x16x32_f16 v[32:35], v[160:163], v[188:191], v[32:35]
	s_waitcnt vmcnt(3) lgkmcnt(0)
	s_barrier
	s_add_i32 s53, s52, 0x6000
	s_cmp_lg_u32 s52, 0x12000
	s_cselect_b32 s53, s53, 0
	v_add_u32_e32 v168, s53, v165
	v_add_u32_e32 v169, s53, v164
	v_mfma_f32_16x16x32_f16 v[36:39], v[148:151], v[192:195], v[36:39]
	ds_read_b128 v[132:135], v168 offset:16
	ds_read_b128 v[184:187], v169 offset:16
	v_mfma_f32_16x16x32_f16 v[40:43], v[152:155], v[192:195], v[40:43]
	ds_read_b128 v[136:139], v168 offset:1040
	ds_read_b128 v[188:191], v169 offset:1040
	v_mfma_f32_16x16x32_f16 v[44:47], v[156:159], v[192:195], v[44:47]
	ds_read_b128 v[140:143], v168 offset:2064
	v_mfma_f32_16x16x32_f16 v[48:51], v[160:163], v[192:195], v[48:51]
	ds_read_b128 v[144:147], v168 offset:3088
	v_mfma_f32_16x16x32_f16 v[52:55], v[148:151], v[196:199], v[52:55]
	v_mfma_f32_16x16x32_f16 v[56:59], v[152:155], v[196:199], v[56:59]
	v_mfma_f32_16x16x32_f16 v[60:63], v[156:159], v[196:199], v[60:63]
	v_mfma_f32_16x16x32_f16 v[64:67], v[160:163], v[196:199], v[64:67]
	s_waitcnt lgkmcnt(0)
	s_mov_b32 s52, s53
	v_add_u32_e32 v169, s52, v164
	v_mfma_f32_16x16x32_f16 v[4:7], v[132:135], v[184:187], v[4:7]
	ds_read_b128 v[192:195], v169 offset:2064
	v_mfma_f32_16x16x32_f16 v[8:11], v[136:139], v[184:187], v[8:11]
	ds_read_b128 v[196:199], v169 offset:3088
	v_mfma_f32_16x16x32_f16 v[12:15], v[140:143], v[184:187], v[12:15]
	v_mfma_f32_16x16x32_f16 v[16:19], v[144:147], v[184:187], v[16:19]
	v_mfma_f32_16x16x32_f16 v[20:23], v[132:135], v[188:191], v[20:23]
	v_mfma_f32_16x16x32_f16 v[24:27], v[136:139], v[188:191], v[24:27]
	v_mfma_f32_16x16x32_f16 v[28:31], v[140:143], v[188:191], v[28:31]
	v_mfma_f32_16x16x32_f16 v[32:35], v[144:147], v[188:191], v[32:35]
	s_waitcnt vmcnt(0) lgkmcnt(0)
	s_barrier
	s_add_i32 s53, s52, 0x6000
	s_cmp_lg_u32 s52, 0x12000
	s_cselect_b32 s53, s53, 0
	v_add_u32_e32 v168, s53, v165
	v_add_u32_e32 v169, s53, v164
	v_mfma_f32_16x16x32_f16 v[36:39], v[132:135], v[192:195], v[36:39]
	ds_read_b128 v[148:151], v168 offset:16
	ds_read_b128 v[184:187], v169 offset:16
	v_mfma_f32_16x16x32_f16 v[40:43], v[136:139], v[192:195], v[40:43]
	ds_read_b128 v[152:155], v168 offset:1040
	ds_read_b128 v[188:191], v169 offset:1040
	v_mfma_f32_16x16x32_f16 v[44:47], v[140:143], v[192:195], v[44:47]
	ds_read_b128 v[156:159], v168 offset:2064
	v_mfma_f32_16x16x32_f16 v[48:51], v[144:147], v[192:195], v[48:51]
	ds_read_b128 v[160:163], v168 offset:3088
	v_mfma_f32_16x16x32_f16 v[52:55], v[132:135], v[196:199], v[52:55]
	v_mfma_f32_16x16x32_f16 v[56:59], v[136:139], v[196:199], v[56:59]
	v_mfma_f32_16x16x32_f16 v[60:63], v[140:143], v[196:199], v[60:63]
	v_mfma_f32_16x16x32_f16 v[64:67], v[144:147], v[196:199], v[64:67]
	s_waitcnt lgkmcnt(0)
	s_mov_b32 s52, s53
	v_add_u32_e32 v169, s52, v164
	v_mfma_f32_16x16x32_f16 v[4:7], v[148:151], v[184:187], v[4:7]
	ds_read_b128 v[192:195], v169 offset:2064
	v_mfma_f32_16x16x32_f16 v[8:11], v[152:155], v[184:187], v[8:11]
	ds_read_b128 v[196:199], v169 offset:3088
	v_mfma_f32_16x16x32_f16 v[12:15], v[156:159], v[184:187], v[12:15]
	v_mfma_f32_16x16x32_f16 v[16:19], v[160:163], v[184:187], v[16:19]
	v_mfma_f32_16x16x32_f16 v[20:23], v[148:151], v[188:191], v[20:23]
	v_mfma_f32_16x16x32_f16 v[24:27], v[152:155], v[188:191], v[24:27]
	v_mfma_f32_16x16x32_f16 v[28:31], v[156:159], v[188:191], v[28:31]
	v_mfma_f32_16x16x32_f16 v[32:35], v[160:163], v[188:191], v[32:35]
	s_waitcnt lgkmcnt(0)
	s_barrier
	v_mfma_f32_16x16x32_f16 v[36:39], v[148:151], v[192:195], v[36:39]
	v_mfma_f32_16x16x32_f16 v[40:43], v[152:155], v[192:195], v[40:43]
	v_mfma_f32_16x16x32_f16 v[44:47], v[156:159], v[192:195], v[44:47]
	v_mfma_f32_16x16x32_f16 v[48:51], v[160:163], v[192:195], v[48:51]
	v_mfma_f32_16x16x32_f16 v[52:55], v[148:151], v[196:199], v[52:55]
	v_mfma_f32_16x16x32_f16 v[56:59], v[152:155], v[196:199], v[56:59]
	v_mfma_f32_16x16x32_f16 v[60:63], v[156:159], v[196:199], v[60:63]
	v_mfma_f32_16x16x32_f16 v[64:67], v[160:163], v[196:199], v[64:67]
	s_sub_u32 s77, s25, 0x1000
	s_lshr_b32 s77, s77, 12
	s_add_u32 s77, s77, 1
	s_cmp_lt_u32 s25, 0x1000
	s_cselect_b32 s77, 0, s77
	s_mul_i32 s77, s77, 0x6000
	s_add_u32 s68, s28, s77
	s_addc_u32 s69, s29, 0
	s_add_u32 s68, s68, 0x20000
	s_addc_u32 s69, s69, 0
	s_lshl_b32 s82, s25, 11
	s_add_u32 s80, s46, s82
	s_addc_u32 s81, s47, 0
	s_lshl_b32 s82, s30, 1
	s_add_u32 s80, s80, s82
	s_addc_u32 s81, s81, 0
	v_and_b32_e32 v172, 15, v200
	v_bfe_u32 v173, v200, 4, 2
	v_bfe_u32 v174, v200, 6, 1
	v_bfe_u32 v175, v200, 7, 2
	v_lshlrev_b32_e32 v176, 6, v174
	v_lshl_or_b32 v176, v173, 2, v176
	v_lshl_or_b32 v175, v175, 6, v172
	v_lshlrev_b32_e32 v175, 11, v175
	v_lshl_add_u32 v177, v176, 1, v175
	v_add_u32_e32 v176, s30, v176
	v_lshlrev_b32_e32 v176, 2, v176
	global_load_dwordx4 v[132:135], v176, s[68:69]
	global_load_dwordx4 v[136:139], v176, s[68:69] offset:64
	global_load_dwordx4 v[140:143], v176, s[68:69] offset:128
	global_load_dwordx4 v[144:147], v176, s[68:69] offset:192
	v_and_b32_e32 v172, 1, v173
	v_mul_u32_u24_e32 v172, 24, v172
	v_add_u32_e32 v177, v177, v172
	v_mov_b32_e32 v178, v177
	global_load_dwordx4 v[184:187], v178, s[80:81]
	global_load_dwordx4 v[188:191], v178, s[80:81] offset:64
	v_add_u32_e32 v178, 0x8000, v178
	global_load_dwordx4 v[192:195], v178, s[80:81]
	global_load_dwordx4 v[196:199], v178, s[80:81] offset:64
	s_waitcnt vmcnt(3)
	v_permlane16_swap_b32_e32 v184, v186
	v_permlane16_swap_b32_e32 v185, v187
	v_cvt_f32_f16_e32 v164, v184
	v_cvt_f32_f16_sdwa v165, v184 dst_sel:DWORD dst_unused:UNUSED_PAD src0_sel:WORD_1
	v_cvt_f32_f16_e32 v166, v185
	v_cvt_f32_f16_sdwa v167, v185 dst_sel:DWORD dst_unused:UNUSED_PAD src0_sel:WORD_1
	v_pk_mul_f32 v[164:165], v[164:165], s[84:85] op_sel_hi:[1,0]
	v_pk_mul_f32 v[166:167], v[166:167], s[84:85] op_sel_hi:[1,0]
	v_pk_fma_f32 v[4:5], v[4:5], v[132:133], v[164:165]
	v_pk_fma_f32 v[6:7], v[6:7], v[134:135], v[166:167]
	v_cvt_pk_f16_f32 v172, v4, v5
	v_cvt_pk_f16_f32 v173, v6, v7
	v_cvt_f32_f16_e32 v164, v186
	v_cvt_f32_f16_sdwa v165, v186 dst_sel:DWORD dst_unused:UNUSED_PAD src0_sel:WORD_1
	v_cvt_f32_f16_e32 v166, v187
	v_cvt_f32_f16_sdwa v167, v187 dst_sel:DWORD dst_unused:UNUSED_PAD src0_sel:WORD_1
	v_pk_mul_f32 v[164:165], v[164:165], s[84:85] op_sel_hi:[1,0]
	v_pk_mul_f32 v[166:167], v[166:167], s[84:85] op_sel_hi:[1,0]
	v_pk_fma_f32 v[8:9], v[8:9], v[136:137], v[164:165]
	v_pk_fma_f32 v[10:11], v[10:11], v[138:139], v[166:167]
	v_cvt_pk_f16_f32 v174, v8, v9
	v_cvt_pk_f16_f32 v175, v10, v11
	s_nop 1
	v_permlane16_swap_b32_e32 v172, v174
	v_permlane16_swap_b32_e32 v173, v175
	global_store_dwordx4 v177, v[172:175], s[80:81]
	s_waitcnt vmcnt(3)
	v_permlane16_swap_b32_e32 v188, v190
	v_permlane16_swap_b32_e32 v189, v191
	v_cvt_f32_f16_e32 v164, v188
	v_cvt_f32_f16_sdwa v165, v188 dst_sel:DWORD dst_unused:UNUSED_PAD src0_sel:WORD_1
	v_cvt_f32_f16_e32 v166, v189
	v_cvt_f32_f16_sdwa v167, v189 dst_sel:DWORD dst_unused:UNUSED_PAD src0_sel:WORD_1
	v_pk_mul_f32 v[164:165], v[164:165], s[84:85] op_sel_hi:[1,0]
	v_pk_mul_f32 v[166:167], v[166:167], s[84:85] op_sel_hi:[1,0]
	v_pk_fma_f32 v[12:13], v[12:13], v[140:141], v[164:165]
	v_pk_fma_f32 v[14:15], v[14:15], v[142:143], v[166:167]
	v_cvt_pk_f16_f32 v228, v12, v13
	v_cvt_pk_f16_f32 v229, v14, v15
	v_cvt_f32_f16_e32 v164, v190
	v_cvt_f32_f16_sdwa v165, v190 dst_sel:DWORD dst_unused:UNUSED_PAD src0_sel:WORD_1
	v_cvt_f32_f16_e32 v166, v191
	v_cvt_f32_f16_sdwa v167, v191 dst_sel:DWORD dst_unused:UNUSED_PAD src0_sel:WORD_1
	v_pk_mul_f32 v[164:165], v[164:165], s[84:85] op_sel_hi:[1,0]
	v_pk_mul_f32 v[166:167], v[166:167], s[84:85] op_sel_hi:[1,0]
	v_pk_fma_f32 v[16:17], v[16:17], v[144:145], v[164:165]
	v_pk_fma_f32 v[18:19], v[18:19], v[146:147], v[166:167]
	v_cvt_pk_f16_f32 v230, v16, v17
	v_cvt_pk_f16_f32 v231, v18, v19
	s_nop 1
	v_permlane16_swap_b32_e32 v228, v230
	v_permlane16_swap_b32_e32 v229, v231
	global_store_dwordx4 v177, v[228:231], s[80:81] offset:64
	v_add_u32_e32 v177, 0x8000, v177
	v_add_u32_e32 v178, 0x8000, v178
	global_load_dwordx4 v[184:187], v178, s[80:81]
	global_load_dwordx4 v[188:191], v178, s[80:81] offset:64
	s_waitcnt vmcnt(5)
	v_permlane16_swap_b32_e32 v192, v194
	v_permlane16_swap_b32_e32 v193, v195
	v_cvt_f32_f16_e32 v164, v192
	v_cvt_f32_f16_sdwa v165, v192 dst_sel:DWORD dst_unused:UNUSED_PAD src0_sel:WORD_1
	v_cvt_f32_f16_e32 v166, v193
	v_cvt_f32_f16_sdwa v167, v193 dst_sel:DWORD dst_unused:UNUSED_PAD src0_sel:WORD_1
	v_pk_mul_f32 v[164:165], v[164:165], s[84:85] op_sel_hi:[1,0]
	v_pk_mul_f32 v[166:167], v[166:167], s[84:85] op_sel_hi:[1,0]
	v_pk_fma_f32 v[20:21], v[20:21], v[132:133], v[164:165]
	v_pk_fma_f32 v[22:23], v[22:23], v[134:135], v[166:167]
	v_cvt_pk_f16_f32 v172, v20, v21
	v_cvt_pk_f16_f32 v173, v22, v23
	v_cvt_f32_f16_e32 v164, v194
	v_cvt_f32_f16_sdwa v165, v194 dst_sel:DWORD dst_unused:UNUSED_PAD src0_sel:WORD_1
	v_cvt_f32_f16_e32 v166, v195
	v_cvt_f32_f16_sdwa v167, v195 dst_sel:DWORD dst_unused:UNUSED_PAD src0_sel:WORD_1
	v_pk_mul_f32 v[164:165], v[164:165], s[84:85] op_sel_hi:[1,0]
	v_pk_mul_f32 v[166:167], v[166:167], s[84:85] op_sel_hi:[1,0]
	v_pk_fma_f32 v[24:25], v[24:25], v[136:137], v[164:165]
	v_pk_fma_f32 v[26:27], v[26:27], v[138:139], v[166:167]
	v_cvt_pk_f16_f32 v174, v24, v25
	v_cvt_pk_f16_f32 v175, v26, v27
	s_nop 1
	v_permlane16_swap_b32_e32 v172, v174
	v_permlane16_swap_b32_e32 v173, v175
	global_store_dwordx4 v177, v[172:175], s[80:81]
	s_waitcnt vmcnt(5)
	v_permlane16_swap_b32_e32 v196, v198
	v_permlane16_swap_b32_e32 v197, v199
	v_cvt_f32_f16_e32 v164, v196
	v_cvt_f32_f16_sdwa v165, v196 dst_sel:DWORD dst_unused:UNUSED_PAD src0_sel:WORD_1
	v_cvt_f32_f16_e32 v166, v197
	v_cvt_f32_f16_sdwa v167, v197 dst_sel:DWORD dst_unused:UNUSED_PAD src0_sel:WORD_1
	v_pk_mul_f32 v[164:165], v[164:165], s[84:85] op_sel_hi:[1,0]
	v_pk_mul_f32 v[166:167], v[166:167], s[84:85] op_sel_hi:[1,0]
	v_pk_fma_f32 v[28:29], v[28:29], v[140:141], v[164:165]
	v_pk_fma_f32 v[30:31], v[30:31], v[142:143], v[166:167]
	v_cvt_pk_f16_f32 v228, v28, v29
	v_cvt_pk_f16_f32 v229, v30, v31
	v_cvt_f32_f16_e32 v164, v198
	v_cvt_f32_f16_sdwa v165, v198 dst_sel:DWORD dst_unused:UNUSED_PAD src0_sel:WORD_1
	v_cvt_f32_f16_e32 v166, v199
	v_cvt_f32_f16_sdwa v167, v199 dst_sel:DWORD dst_unused:UNUSED_PAD src0_sel:WORD_1
	v_pk_mul_f32 v[164:165], v[164:165], s[84:85] op_sel_hi:[1,0]
	v_pk_mul_f32 v[166:167], v[166:167], s[84:85] op_sel_hi:[1,0]
	v_pk_fma_f32 v[32:33], v[32:33], v[144:145], v[164:165]
	v_pk_fma_f32 v[34:35], v[34:35], v[146:147], v[166:167]
	v_cvt_pk_f16_f32 v230, v32, v33
	v_cvt_pk_f16_f32 v231, v34, v35
	s_nop 1
	v_permlane16_swap_b32_e32 v228, v230
	v_permlane16_swap_b32_e32 v229, v231
	global_store_dwordx4 v177, v[228:231], s[80:81] offset:64
	v_add_u32_e32 v177, 0x8000, v177
	v_add_u32_e32 v178, 0x8000, v178
	global_load_dwordx4 v[192:195], v178, s[80:81]
	global_load_dwordx4 v[196:199], v178, s[80:81] offset:64
	s_waitcnt vmcnt(5)
	v_permlane16_swap_b32_e32 v184, v186
	v_permlane16_swap_b32_e32 v185, v187
	v_cvt_f32_f16_e32 v164, v184
	v_cvt_f32_f16_sdwa v165, v184 dst_sel:DWORD dst_unused:UNUSED_PAD src0_sel:WORD_1
	v_cvt_f32_f16_e32 v166, v185
	v_cvt_f32_f16_sdwa v167, v185 dst_sel:DWORD dst_unused:UNUSED_PAD src0_sel:WORD_1
	v_pk_mul_f32 v[164:165], v[164:165], s[84:85] op_sel_hi:[1,0]
	v_pk_mul_f32 v[166:167], v[166:167], s[84:85] op_sel_hi:[1,0]
	v_pk_fma_f32 v[36:37], v[36:37], v[132:133], v[164:165]
	v_pk_fma_f32 v[38:39], v[38:39], v[134:135], v[166:167]
	v_cvt_pk_f16_f32 v172, v36, v37
	v_cvt_pk_f16_f32 v173, v38, v39
	v_cvt_f32_f16_e32 v164, v186
	v_cvt_f32_f16_sdwa v165, v186 dst_sel:DWORD dst_unused:UNUSED_PAD src0_sel:WORD_1
	v_cvt_f32_f16_e32 v166, v187
	v_cvt_f32_f16_sdwa v167, v187 dst_sel:DWORD dst_unused:UNUSED_PAD src0_sel:WORD_1
	v_pk_mul_f32 v[164:165], v[164:165], s[84:85] op_sel_hi:[1,0]
	v_pk_mul_f32 v[166:167], v[166:167], s[84:85] op_sel_hi:[1,0]
	v_pk_fma_f32 v[40:41], v[40:41], v[136:137], v[164:165]
	v_pk_fma_f32 v[42:43], v[42:43], v[138:139], v[166:167]
	v_cvt_pk_f16_f32 v174, v40, v41
	v_cvt_pk_f16_f32 v175, v42, v43
	s_nop 1
	v_permlane16_swap_b32_e32 v172, v174
	v_permlane16_swap_b32_e32 v173, v175
	global_store_dwordx4 v177, v[172:175], s[80:81]
	s_waitcnt vmcnt(5)
	v_permlane16_swap_b32_e32 v188, v190
	v_permlane16_swap_b32_e32 v189, v191
	v_cvt_f32_f16_e32 v164, v188
	v_cvt_f32_f16_sdwa v165, v188 dst_sel:DWORD dst_unused:UNUSED_PAD src0_sel:WORD_1
	v_cvt_f32_f16_e32 v166, v189
	v_cvt_f32_f16_sdwa v167, v189 dst_sel:DWORD dst_unused:UNUSED_PAD src0_sel:WORD_1
	v_pk_mul_f32 v[164:165], v[164:165], s[84:85] op_sel_hi:[1,0]
	v_pk_mul_f32 v[166:167], v[166:167], s[84:85] op_sel_hi:[1,0]
	v_pk_fma_f32 v[44:45], v[44:45], v[140:141], v[164:165]
	v_pk_fma_f32 v[46:47], v[46:47], v[142:143], v[166:167]
	v_cvt_pk_f16_f32 v228, v44, v45
	v_cvt_pk_f16_f32 v229, v46, v47
	v_cvt_f32_f16_e32 v164, v190
	v_cvt_f32_f16_sdwa v165, v190 dst_sel:DWORD dst_unused:UNUSED_PAD src0_sel:WORD_1
	v_cvt_f32_f16_e32 v166, v191
	v_cvt_f32_f16_sdwa v167, v191 dst_sel:DWORD dst_unused:UNUSED_PAD src0_sel:WORD_1
	v_pk_mul_f32 v[164:165], v[164:165], s[84:85] op_sel_hi:[1,0]
	v_pk_mul_f32 v[166:167], v[166:167], s[84:85] op_sel_hi:[1,0]
	v_pk_fma_f32 v[48:49], v[48:49], v[144:145], v[164:165]
	v_pk_fma_f32 v[50:51], v[50:51], v[146:147], v[166:167]
	v_cvt_pk_f16_f32 v230, v48, v49
	v_cvt_pk_f16_f32 v231, v50, v51
	s_nop 1
	v_permlane16_swap_b32_e32 v228, v230
	v_permlane16_swap_b32_e32 v229, v231
	global_store_dwordx4 v177, v[228:231], s[80:81] offset:64
	v_add_u32_e32 v177, 0x8000, v177
	s_waitcnt vmcnt(3)
	v_permlane16_swap_b32_e32 v192, v194
	v_permlane16_swap_b32_e32 v193, v195
	v_cvt_f32_f16_e32 v164, v192
	v_cvt_f32_f16_sdwa v165, v192 dst_sel:DWORD dst_unused:UNUSED_PAD src0_sel:WORD_1
	v_cvt_f32_f16_e32 v166, v193
	v_cvt_f32_f16_sdwa v167, v193 dst_sel:DWORD dst_unused:UNUSED_PAD src0_sel:WORD_1
	v_pk_mul_f32 v[164:165], v[164:165], s[84:85] op_sel_hi:[1,0]
	v_pk_mul_f32 v[166:167], v[166:167], s[84:85] op_sel_hi:[1,0]
	v_pk_fma_f32 v[52:53], v[52:53], v[132:133], v[164:165]
	v_pk_fma_f32 v[54:55], v[54:55], v[134:135], v[166:167]
	v_cvt_pk_f16_f32 v172, v52, v53
	v_cvt_pk_f16_f32 v173, v54, v55
	v_cvt_f32_f16_e32 v164, v194
	v_cvt_f32_f16_sdwa v165, v194 dst_sel:DWORD dst_unused:UNUSED_PAD src0_sel:WORD_1
	v_cvt_f32_f16_e32 v166, v195
	v_cvt_f32_f16_sdwa v167, v195 dst_sel:DWORD dst_unused:UNUSED_PAD src0_sel:WORD_1
	v_pk_mul_f32 v[164:165], v[164:165], s[84:85] op_sel_hi:[1,0]
	v_pk_mul_f32 v[166:167], v[166:167], s[84:85] op_sel_hi:[1,0]
	v_pk_fma_f32 v[56:57], v[56:57], v[136:137], v[164:165]
	v_pk_fma_f32 v[58:59], v[58:59], v[138:139], v[166:167]
	v_cvt_pk_f16_f32 v174, v56, v57
	v_cvt_pk_f16_f32 v175, v58, v59
	s_nop 1
	v_permlane16_swap_b32_e32 v172, v174
	v_permlane16_swap_b32_e32 v173, v175
	global_store_dwordx4 v177, v[172:175], s[80:81]
	s_waitcnt vmcnt(3)
	v_permlane16_swap_b32_e32 v196, v198
	v_permlane16_swap_b32_e32 v197, v199
	v_cvt_f32_f16_e32 v164, v196
	v_cvt_f32_f16_sdwa v165, v196 dst_sel:DWORD dst_unused:UNUSED_PAD src0_sel:WORD_1
	v_cvt_f32_f16_e32 v166, v197
	v_cvt_f32_f16_sdwa v167, v197 dst_sel:DWORD dst_unused:UNUSED_PAD src0_sel:WORD_1
	v_pk_mul_f32 v[164:165], v[164:165], s[84:85] op_sel_hi:[1,0]
	v_pk_mul_f32 v[166:167], v[166:167], s[84:85] op_sel_hi:[1,0]
	v_pk_fma_f32 v[60:61], v[60:61], v[140:141], v[164:165]
	v_pk_fma_f32 v[62:63], v[62:63], v[142:143], v[166:167]
	v_cvt_pk_f16_f32 v228, v60, v61
	v_cvt_pk_f16_f32 v229, v62, v63
	v_cvt_f32_f16_e32 v164, v198
	v_cvt_f32_f16_sdwa v165, v198 dst_sel:DWORD dst_unused:UNUSED_PAD src0_sel:WORD_1
	v_cvt_f32_f16_e32 v166, v199
	v_cvt_f32_f16_sdwa v167, v199 dst_sel:DWORD dst_unused:UNUSED_PAD src0_sel:WORD_1
	v_pk_mul_f32 v[164:165], v[164:165], s[84:85] op_sel_hi:[1,0]
	v_pk_mul_f32 v[166:167], v[166:167], s[84:85] op_sel_hi:[1,0]
	v_pk_fma_f32 v[64:65], v[64:65], v[144:145], v[164:165]
	v_pk_fma_f32 v[66:67], v[66:67], v[146:147], v[166:167]
	v_cvt_pk_f16_f32 v230, v64, v65
	v_cvt_pk_f16_f32 v231, v66, v67
	s_nop 1
	v_permlane16_swap_b32_e32 v228, v230
	v_permlane16_swap_b32_e32 v229, v231
	global_store_dwordx4 v177, v[228:231], s[80:81] offset:64
	s_nop 1
	s_add_i32 s24, s24, s64
	s_cmpk_gt_i32 s24, 0x27f
	s_cbranch_scc1 .LBB0_177
	s_branch .LBB0_164

.Lt_mlp2an:
	v_add_u32_e32 v169, s35, v164
	v_mfma_f32_16x16x32_f16 v[4:7], v[132:135], v[184:187], v[4:7]
	ds_read_b128 v[192:195], v169 offset:2064
	v_mfma_f32_16x16x32_f16 v[8:11], v[136:139], v[184:187], v[8:11]
	ds_read_b128 v[196:199], v169 offset:3088
	v_mfma_f32_16x16x32_f16 v[12:15], v[140:143], v[184:187], v[12:15]
	v_mfma_f32_16x16x32_f16 v[16:19], v[144:147], v[184:187], v[16:19]
	v_mfma_f32_16x16x32_f16 v[20:23], v[132:135], v[188:191], v[20:23]
	v_mfma_f32_16x16x32_f16 v[24:27], v[136:139], v[188:191], v[24:27]
	v_mfma_f32_16x16x32_f16 v[28:31], v[140:143], v[188:191], v[28:31]
	v_mfma_f32_16x16x32_f16 v[32:35], v[144:147], v[188:191], v[32:35]
	s_waitcnt vmcnt(6) lgkmcnt(0)
	s_barrier
	s_add_i32 s53, s35, 0x6000
	s_cmp_lg_u32 s35, 0x12000
	s_cselect_b32 s53, s53, 0
	v_add_u32_e32 v168, s53, v165
	v_add_u32_e32 v169, s53, v164
	v_mfma_f32_16x16x32_f16 v[36:39], v[132:135], v[192:195], v[36:39]
	ds_read_b128 v[148:151], v168 offset:16
	ds_read_b128 v[184:187], v169 offset:16
	v_mfma_f32_16x16x32_f16 v[40:43], v[136:139], v[192:195], v[40:43]
	ds_read_b128 v[152:155], v168 offset:1040
	ds_read_b128 v[188:191], v169 offset:1040
	v_mfma_f32_16x16x32_f16 v[44:47], v[140:143], v[192:195], v[44:47]
	ds_read_b128 v[156:159], v168 offset:2064
	v_mfma_f32_16x16x32_f16 v[48:51], v[144:147], v[192:195], v[48:51]
	ds_read_b128 v[160:163], v168 offset:3088
	v_mfma_f32_16x16x32_f16 v[52:55], v[132:135], v[196:199], v[52:55]
	s_add_u32 m0, s25, s35
	s_nop 0
	global_load_lds_dwordx4 v170, s[50:51]
	v_mfma_f32_16x16x32_f16 v[56:59], v[136:139], v[196:199], v[56:59]
	s_add_u32 m0, s25, s35
	s_add_u32 m0, m0, 0x400
	s_nop 0
	global_load_lds_dwordx4 v171, s[50:51]
	v_mfma_f32_16x16x32_f16 v[60:63], v[140:143], v[196:199], v[60:63]
	s_add_u32 m0, s32, s35
	s_nop 0
	global_load_lds_dwordx4 v170, s[54:55]
	v_mfma_f32_16x16x32_f16 v[64:67], v[144:147], v[196:199], v[64:67]
	s_waitcnt lgkmcnt(0)
	s_mov_b32 s35, s53
	s_add_u32 s50, s50, 64
	s_addc_u32 s51, s51, 0
	s_add_u32 s54, s54, 64
	s_addc_u32 s55, s55, 0
	v_add_u32_e32 v169, s35, v164
	v_mfma_f32_16x16x32_f16 v[4:7], v[148:151], v[184:187], v[4:7]
	ds_read_b128 v[192:195], v169 offset:2064
	v_mfma_f32_16x16x32_f16 v[8:11], v[152:155], v[184:187], v[8:11]
	ds_read_b128 v[196:199], v169 offset:3088
	v_mfma_f32_16x16x32_f16 v[12:15], v[156:159], v[184:187], v[12:15]
	v_mfma_f32_16x16x32_f16 v[16:19], v[160:163], v[184:187], v[16:19]
	v_mfma_f32_16x16x32_f16 v[20:23], v[148:151], v[188:191], v[20:23]
	v_mfma_f32_16x16x32_f16 v[24:27], v[152:155], v[188:191], v[24:27]
	v_mfma_f32_16x16x32_f16 v[28:31], v[156:159], v[188:191], v[28:31]
	v_mfma_f32_16x16x32_f16 v[32:35], v[160:163], v[188:191], v[32:35]
	s_waitcnt vmcnt(6) lgkmcnt(0)
	s_barrier
	s_add_i32 s53, s35, 0x6000
	s_cmp_lg_u32 s35, 0x12000
	s_cselect_b32 s53, s53, 0
	v_add_u32_e32 v168, s53, v165
	v_add_u32_e32 v169, s53, v164
	v_mfma_f32_16x16x32_f16 v[36:39], v[148:151], v[192:195], v[36:39]
	ds_read_b128 v[132:135], v168 offset:16
	ds_read_b128 v[184:187], v169 offset:16
	v_mfma_f32_16x16x32_f16 v[40:43], v[152:155], v[192:195], v[40:43]
	ds_read_b128 v[136:139], v168 offset:1040
	ds_read_b128 v[188:191], v169 offset:1040
	v_mfma_f32_16x16x32_f16 v[44:47], v[156:159], v[192:195], v[44:47]
	ds_read_b128 v[140:143], v168 offset:2064
	v_mfma_f32_16x16x32_f16 v[48:51], v[160:163], v[192:195], v[48:51]
	ds_read_b128 v[144:147], v168 offset:3088
	v_mfma_f32_16x16x32_f16 v[52:55], v[148:151], v[196:199], v[52:55]
	s_add_u32 m0, s25, s35
	s_nop 0
	global_load_lds_dwordx4 v170, s[50:51]
	v_mfma_f32_16x16x32_f16 v[56:59], v[152:155], v[196:199], v[56:59]
	s_add_u32 m0, s25, s35
	s_add_u32 m0, m0, 0x400
	s_nop 0
	global_load_lds_dwordx4 v171, s[50:51]
	v_mfma_f32_16x16x32_f16 v[60:63], v[156:159], v[196:199], v[60:63]
	s_add_u32 m0, s32, s35
	s_nop 0
	global_load_lds_dwordx4 v170, s[54:55]
	v_mfma_f32_16x16x32_f16 v[64:67], v[160:163], v[196:199], v[64:67]
	s_waitcnt lgkmcnt(0)
	s_mov_b32 s35, s53
	s_add_u32 s50, s50, 64
	s_addc_u32 s51, s51, 0
	s_add_u32 s54, s54, 64
	s_addc_u32 s55, s55, 0
	s_add_i32 s65, s65, 2
	s_cmp_lt_u32 s65, 124
	s_cbranch_scc1 .Lt_mlp2an
	v_add_u32_e32 v169, s35, v164
	v_mfma_f32_16x16x32_f16 v[4:7], v[132:135], v[184:187], v[4:7]
	ds_read_b128 v[192:195], v169 offset:2064
	v_mfma_f32_16x16x32_f16 v[8:11], v[136:139], v[184:187], v[8:11]
	ds_read_b128 v[196:199], v169 offset:3088
	v_mfma_f32_16x16x32_f16 v[12:15], v[140:143], v[184:187], v[12:15]
	v_mfma_f32_16x16x32_f16 v[16:19], v[144:147], v[184:187], v[16:19]
	v_mfma_f32_16x16x32_f16 v[20:23], v[132:135], v[188:191], v[20:23]
	v_mfma_f32_16x16x32_f16 v[24:27], v[136:139], v[188:191], v[24:27]
	v_mfma_f32_16x16x32_f16 v[28:31], v[140:143], v[188:191], v[28:31]
	v_mfma_f32_16x16x32_f16 v[32:35], v[144:147], v[188:191], v[32:35]
	s_waitcnt vmcnt(6) lgkmcnt(0)
	s_barrier
	s_add_i32 s53, s35, 0x6000
	s_cmp_lg_u32 s35, 0x12000
	s_cselect_b32 s53, s53, 0
	v_add_u32_e32 v168, s53, v165
	v_add_u32_e32 v169, s53, v164
	v_mfma_f32_16x16x32_f16 v[36:39], v[132:135], v[192:195], v[36:39]
	ds_read_b128 v[148:151], v168 offset:16
	ds_read_b128 v[184:187], v169 offset:16
	v_mfma_f32_16x16x32_f16 v[40:43], v[136:139], v[192:195], v[40:43]
	ds_read_b128 v[152:155], v168 offset:1040
	ds_read_b128 v[188:191], v169 offset:1040
	v_mfma_f32_16x16x32_f16 v[44:47], v[140:143], v[192:195], v[44:47]
	ds_read_b128 v[156:159], v168 offset:2064
	v_mfma_f32_16x16x32_f16 v[48:51], v[144:147], v[192:195], v[48:51]
	ds_read_b128 v[160:163], v168 offset:3088
	v_mfma_f32_16x16x32_f16 v[52:55], v[132:135], v[196:199], v[52:55]
	v_mfma_f32_16x16x32_f16 v[56:59], v[136:139], v[196:199], v[56:59]
	v_mfma_f32_16x16x32_f16 v[60:63], v[140:143], v[196:199], v[60:63]
	v_mfma_f32_16x16x32_f16 v[64:67], v[144:147], v[196:199], v[64:67]
	s_waitcnt lgkmcnt(0)
	s_mov_b32 s35, s53
	v_add_u32_e32 v169, s35, v164
	v_mfma_f32_16x16x32_f16 v[4:7], v[148:151], v[184:187], v[4:7]
	ds_read_b128 v[192:195], v169 offset:2064
	v_mfma_f32_16x16x32_f16 v[8:11], v[152:155], v[184:187], v[8:11]
	ds_read_b128 v[196:199], v169 offset:3088
	v_mfma_f32_16x16x32_f16 v[12:15], v[156:159], v[184:187], v[12:15]
	v_mfma_f32_16x16x32_f16 v[16:19], v[160:163], v[184:187], v[16:19]
	v_mfma_f32_16x16x32_f16 v[20:23], v[148:151], v[188:191], v[20:23]
	v_mfma_f32_16x16x32_f16 v[24:27], v[152:155], v[188:191], v[24:27]
	v_mfma_f32_16x16x32_f16 v[28:31], v[156:159], v[188:191], v[28:31]
	v_mfma_f32_16x16x32_f16 v[32:35], v[160:163], v[188:191], v[32:35]
	s_waitcnt vmcnt(3) lgkmcnt(0)
	s_barrier
	s_add_i32 s53, s35, 0x6000
	s_cmp_lg_u32 s35, 0x12000
	s_cselect_b32 s53, s53, 0
	v_add_u32_e32 v168, s53, v165
	v_add_u32_e32 v169, s53, v164
	v_mfma_f32_16x16x32_f16 v[36:39], v[148:151], v[192:195], v[36:39]
	ds_read_b128 v[132:135], v168 offset:16
	ds_read_b128 v[184:187], v169 offset:16
	v_mfma_f32_16x16x32_f16 v[40:43], v[152:155], v[192:195], v[40:43]
	ds_read_b128 v[136:139], v168 offset:1040
	ds_read_b128 v[188:191], v169 offset:1040
	v_mfma_f32_16x16x32_f16 v[44:47], v[156:159], v[192:195], v[44:47]
	ds_read_b128 v[140:143], v168 offset:2064
	v_mfma_f32_16x16x32_f16 v[48:51], v[160:163], v[192:195], v[48:51]
	ds_read_b128 v[144:147], v168 offset:3088
	v_mfma_f32_16x16x32_f16 v[52:55], v[148:151], v[196:199], v[52:55]
	v_mfma_f32_16x16x32_f16 v[56:59], v[152:155], v[196:199], v[56:59]
	v_mfma_f32_16x16x32_f16 v[60:63], v[156:159], v[196:199], v[60:63]
	v_mfma_f32_16x16x32_f16 v[64:67], v[160:163], v[196:199], v[64:67]
	s_waitcnt lgkmcnt(0)
	s_mov_b32 s35, s53
	v_add_u32_e32 v169, s35, v164
	v_mfma_f32_16x16x32_f16 v[4:7], v[132:135], v[184:187], v[4:7]
	ds_read_b128 v[192:195], v169 offset:2064
	v_mfma_f32_16x16x32_f16 v[8:11], v[136:139], v[184:187], v[8:11]
	ds_read_b128 v[196:199], v169 offset:3088
	v_mfma_f32_16x16x32_f16 v[12:15], v[140:143], v[184:187], v[12:15]
	v_mfma_f32_16x16x32_f16 v[16:19], v[144:147], v[184:187], v[16:19]
	v_mfma_f32_16x16x32_f16 v[20:23], v[132:135], v[188:191], v[20:23]
	v_mfma_f32_16x16x32_f16 v[24:27], v[136:139], v[188:191], v[24:27]
	v_mfma_f32_16x16x32_f16 v[28:31], v[140:143], v[188:191], v[28:31]
	v_mfma_f32_16x16x32_f16 v[32:35], v[144:147], v[188:191], v[32:35]
	s_waitcnt vmcnt(0) lgkmcnt(0)
	s_barrier
	s_add_i32 s53, s35, 0x6000
	s_cmp_lg_u32 s35, 0x12000
	s_cselect_b32 s53, s53, 0
	v_add_u32_e32 v168, s53, v165
	v_add_u32_e32 v169, s53, v164
	v_mfma_f32_16x16x32_f16 v[36:39], v[132:135], v[192:195], v[36:39]
	ds_read_b128 v[148:151], v168 offset:16
	ds_read_b128 v[184:187], v169 offset:16
	v_mfma_f32_16x16x32_f16 v[40:43], v[136:139], v[192:195], v[40:43]
	ds_read_b128 v[152:155], v168 offset:1040
	ds_read_b128 v[188:191], v169 offset:1040
	v_mfma_f32_16x16x32_f16 v[44:47], v[140:143], v[192:195], v[44:47]
	ds_read_b128 v[156:159], v168 offset:2064
	v_mfma_f32_16x16x32_f16 v[48:51], v[144:147], v[192:195], v[48:51]
	ds_read_b128 v[160:163], v168 offset:3088
	v_mfma_f32_16x16x32_f16 v[52:55], v[132:135], v[196:199], v[52:55]
	v_mfma_f32_16x16x32_f16 v[56:59], v[136:139], v[196:199], v[56:59]
	v_mfma_f32_16x16x32_f16 v[60:63], v[140:143], v[196:199], v[60:63]
	v_mfma_f32_16x16x32_f16 v[64:67], v[144:147], v[196:199], v[64:67]
	s_waitcnt lgkmcnt(0)
	s_mov_b32 s35, s53
	v_add_u32_e32 v169, s35, v164
	v_mfma_f32_16x16x32_f16 v[4:7], v[148:151], v[184:187], v[4:7]
	ds_read_b128 v[192:195], v169 offset:2064
	v_mfma_f32_16x16x32_f16 v[8:11], v[152:155], v[184:187], v[8:11]
	ds_read_b128 v[196:199], v169 offset:3088
	v_mfma_f32_16x16x32_f16 v[12:15], v[156:159], v[184:187], v[12:15]
	v_mfma_f32_16x16x32_f16 v[16:19], v[160:163], v[184:187], v[16:19]
	v_mfma_f32_16x16x32_f16 v[20:23], v[148:151], v[188:191], v[20:23]
	v_mfma_f32_16x16x32_f16 v[24:27], v[152:155], v[188:191], v[24:27]
	v_mfma_f32_16x16x32_f16 v[28:31], v[156:159], v[188:191], v[28:31]
	v_mfma_f32_16x16x32_f16 v[32:35], v[160:163], v[188:191], v[32:35]
	s_waitcnt lgkmcnt(0)
	s_barrier
	v_mfma_f32_16x16x32_f16 v[36:39], v[148:151], v[192:195], v[36:39]
	v_mfma_f32_16x16x32_f16 v[40:43], v[152:155], v[192:195], v[40:43]
	v_mfma_f32_16x16x32_f16 v[44:47], v[156:159], v[192:195], v[44:47]
	v_mfma_f32_16x16x32_f16 v[48:51], v[160:163], v[192:195], v[48:51]
	v_mfma_f32_16x16x32_f16 v[52:55], v[148:151], v[196:199], v[52:55]
	v_mfma_f32_16x16x32_f16 v[56:59], v[152:155], v[196:199], v[56:59]
	v_mfma_f32_16x16x32_f16 v[60:63], v[156:159], v[196:199], v[60:63]
	v_mfma_f32_16x16x32_f16 v[64:67], v[160:163], v[196:199], v[64:67]
	s_sub_u32 s77, s34, 0x1000
	s_lshr_b32 s77, s77, 12
	s_add_u32 s77, s77, 1
	s_cmp_lt_u32 s34, 0x1000
	s_cselect_b32 s77, 0, s77
	s_mul_i32 s77, s77, 0x6000
	s_add_u32 s68, s44, s77
	s_addc_u32 s69, s45, 0
	s_add_u32 s68, s68, 0xfa10600
	s_addc_u32 s69, s69, 0
	s_lshl_b32 s82, s34, 11
	s_add_u32 s80, s46, s82
	s_addc_u32 s81, s47, 0
	s_lshl_b32 s82, s30, 1
	s_add_u32 s80, s80, s82
	s_addc_u32 s81, s81, 0
	v_and_b32_e32 v172, 15, v200
	v_bfe_u32 v173, v200, 4, 2
	v_bfe_u32 v174, v200, 6, 1
	v_bfe_u32 v175, v200, 7, 2
	v_lshlrev_b32_e32 v176, 6, v174
	v_lshl_or_b32 v176, v173, 2, v176
	v_lshl_or_b32 v175, v175, 6, v172
	v_lshlrev_b32_e32 v175, 11, v175
	v_lshl_add_u32 v177, v176, 1, v175
	v_add_u32_e32 v176, s30, v176
	v_lshlrev_b32_e32 v176, 2, v176
	global_load_dwordx4 v[132:135], v176, s[68:69]
	global_load_dwordx4 v[136:139], v176, s[68:69] offset:64
	global_load_dwordx4 v[140:143], v176, s[68:69] offset:128
	global_load_dwordx4 v[144:147], v176, s[68:69] offset:192
	v_and_b32_e32 v172, 1, v173
	v_mul_u32_u24_e32 v172, 24, v172
	v_add_u32_e32 v177, v177, v172
	v_mov_b32_e32 v178, v177
	global_load_dwordx4 v[184:187], v178, s[80:81]
	global_load_dwordx4 v[188:191], v178, s[80:81] offset:64
	v_add_u32_e32 v178, 0x8000, v178
	global_load_dwordx4 v[192:195], v178, s[80:81]
	global_load_dwordx4 v[196:199], v178, s[80:81] offset:64
	s_waitcnt vmcnt(3)
	v_permlane16_swap_b32_e32 v184, v186
	v_permlane16_swap_b32_e32 v185, v187
	v_cvt_f32_f16_e32 v164, v184
	v_cvt_f32_f16_sdwa v165, v184 dst_sel:DWORD dst_unused:UNUSED_PAD src0_sel:WORD_1
	v_cvt_f32_f16_e32 v166, v185
	v_cvt_f32_f16_sdwa v167, v185 dst_sel:DWORD dst_unused:UNUSED_PAD src0_sel:WORD_1
	v_pk_mul_f32 v[164:165], v[164:165], s[84:85] op_sel_hi:[1,0]
	v_pk_mul_f32 v[166:167], v[166:167], s[84:85] op_sel_hi:[1,0]
	v_pk_fma_f32 v[4:5], v[4:5], v[132:133], v[164:165]
	v_pk_fma_f32 v[6:7], v[6:7], v[134:135], v[166:167]
	v_cvt_pk_f16_f32 v172, v4, v5
	v_cvt_pk_f16_f32 v173, v6, v7
	v_cvt_f32_f16_e32 v164, v186
	v_cvt_f32_f16_sdwa v165, v186 dst_sel:DWORD dst_unused:UNUSED_PAD src0_sel:WORD_1
	v_cvt_f32_f16_e32 v166, v187
	v_cvt_f32_f16_sdwa v167, v187 dst_sel:DWORD dst_unused:UNUSED_PAD src0_sel:WORD_1
	v_pk_mul_f32 v[164:165], v[164:165], s[84:85] op_sel_hi:[1,0]
	v_pk_mul_f32 v[166:167], v[166:167], s[84:85] op_sel_hi:[1,0]
	v_pk_fma_f32 v[8:9], v[8:9], v[136:137], v[164:165]
	v_pk_fma_f32 v[10:11], v[10:11], v[138:139], v[166:167]
	v_cvt_pk_f16_f32 v174, v8, v9
	v_cvt_pk_f16_f32 v175, v10, v11
	s_nop 1
	v_permlane16_swap_b32_e32 v172, v174
	v_permlane16_swap_b32_e32 v173, v175
	global_store_dwordx4 v177, v[172:175], s[80:81]
	s_waitcnt vmcnt(3)
	v_permlane16_swap_b32_e32 v188, v190
	v_permlane16_swap_b32_e32 v189, v191
	v_cvt_f32_f16_e32 v164, v188
	v_cvt_f32_f16_sdwa v165, v188 dst_sel:DWORD dst_unused:UNUSED_PAD src0_sel:WORD_1
	v_cvt_f32_f16_e32 v166, v189
	v_cvt_f32_f16_sdwa v167, v189 dst_sel:DWORD dst_unused:UNUSED_PAD src0_sel:WORD_1
	v_pk_mul_f32 v[164:165], v[164:165], s[84:85] op_sel_hi:[1,0]
	v_pk_mul_f32 v[166:167], v[166:167], s[84:85] op_sel_hi:[1,0]
	v_pk_fma_f32 v[12:13], v[12:13], v[140:141], v[164:165]
	v_pk_fma_f32 v[14:15], v[14:15], v[142:143], v[166:167]
	v_cvt_pk_f16_f32 v228, v12, v13
	v_cvt_pk_f16_f32 v229, v14, v15
	v_cvt_f32_f16_e32 v164, v190
	v_cvt_f32_f16_sdwa v165, v190 dst_sel:DWORD dst_unused:UNUSED_PAD src0_sel:WORD_1
	v_cvt_f32_f16_e32 v166, v191
	v_cvt_f32_f16_sdwa v167, v191 dst_sel:DWORD dst_unused:UNUSED_PAD src0_sel:WORD_1
	v_pk_mul_f32 v[164:165], v[164:165], s[84:85] op_sel_hi:[1,0]
	v_pk_mul_f32 v[166:167], v[166:167], s[84:85] op_sel_hi:[1,0]
	v_pk_fma_f32 v[16:17], v[16:17], v[144:145], v[164:165]
	v_pk_fma_f32 v[18:19], v[18:19], v[146:147], v[166:167]
	v_cvt_pk_f16_f32 v230, v16, v17
	v_cvt_pk_f16_f32 v231, v18, v19
	s_nop 1
	v_permlane16_swap_b32_e32 v228, v230
	v_permlane16_swap_b32_e32 v229, v231
	global_store_dwordx4 v177, v[228:231], s[80:81] offset:64
	v_add_u32_e32 v177, 0x8000, v177
	v_add_u32_e32 v178, 0x8000, v178
	global_load_dwordx4 v[184:187], v178, s[80:81]
	global_load_dwordx4 v[188:191], v178, s[80:81] offset:64
	s_waitcnt vmcnt(5)
	v_permlane16_swap_b32_e32 v192, v194
	v_permlane16_swap_b32_e32 v193, v195
	v_cvt_f32_f16_e32 v164, v192
	v_cvt_f32_f16_sdwa v165, v192 dst_sel:DWORD dst_unused:UNUSED_PAD src0_sel:WORD_1
	v_cvt_f32_f16_e32 v166, v193
	v_cvt_f32_f16_sdwa v167, v193 dst_sel:DWORD dst_unused:UNUSED_PAD src0_sel:WORD_1
	v_pk_mul_f32 v[164:165], v[164:165], s[84:85] op_sel_hi:[1,0]
	v_pk_mul_f32 v[166:167], v[166:167], s[84:85] op_sel_hi:[1,0]
	v_pk_fma_f32 v[20:21], v[20:21], v[132:133], v[164:165]
	v_pk_fma_f32 v[22:23], v[22:23], v[134:135], v[166:167]
	v_cvt_pk_f16_f32 v172, v20, v21
	v_cvt_pk_f16_f32 v173, v22, v23
	v_cvt_f32_f16_e32 v164, v194
	v_cvt_f32_f16_sdwa v165, v194 dst_sel:DWORD dst_unused:UNUSED_PAD src0_sel:WORD_1
	v_cvt_f32_f16_e32 v166, v195
	v_cvt_f32_f16_sdwa v167, v195 dst_sel:DWORD dst_unused:UNUSED_PAD src0_sel:WORD_1
	v_pk_mul_f32 v[164:165], v[164:165], s[84:85] op_sel_hi:[1,0]
	v_pk_mul_f32 v[166:167], v[166:167], s[84:85] op_sel_hi:[1,0]
	v_pk_fma_f32 v[24:25], v[24:25], v[136:137], v[164:165]
	v_pk_fma_f32 v[26:27], v[26:27], v[138:139], v[166:167]
	v_cvt_pk_f16_f32 v174, v24, v25
	v_cvt_pk_f16_f32 v175, v26, v27
	s_nop 1
	v_permlane16_swap_b32_e32 v172, v174
	v_permlane16_swap_b32_e32 v173, v175
	global_store_dwordx4 v177, v[172:175], s[80:81]
	s_waitcnt vmcnt(5)
	v_permlane16_swap_b32_e32 v196, v198
	v_permlane16_swap_b32_e32 v197, v199
	v_cvt_f32_f16_e32 v164, v196
	v_cvt_f32_f16_sdwa v165, v196 dst_sel:DWORD dst_unused:UNUSED_PAD src0_sel:WORD_1
	v_cvt_f32_f16_e32 v166, v197
	v_cvt_f32_f16_sdwa v167, v197 dst_sel:DWORD dst_unused:UNUSED_PAD src0_sel:WORD_1
	v_pk_mul_f32 v[164:165], v[164:165], s[84:85] op_sel_hi:[1,0]
	v_pk_mul_f32 v[166:167], v[166:167], s[84:85] op_sel_hi:[1,0]
	v_pk_fma_f32 v[28:29], v[28:29], v[140:141], v[164:165]
	v_pk_fma_f32 v[30:31], v[30:31], v[142:143], v[166:167]
	v_cvt_pk_f16_f32 v228, v28, v29
	v_cvt_pk_f16_f32 v229, v30, v31
	v_cvt_f32_f16_e32 v164, v198
	v_cvt_f32_f16_sdwa v165, v198 dst_sel:DWORD dst_unused:UNUSED_PAD src0_sel:WORD_1
	v_cvt_f32_f16_e32 v166, v199
	v_cvt_f32_f16_sdwa v167, v199 dst_sel:DWORD dst_unused:UNUSED_PAD src0_sel:WORD_1
	v_pk_mul_f32 v[164:165], v[164:165], s[84:85] op_sel_hi:[1,0]
	v_pk_mul_f32 v[166:167], v[166:167], s[84:85] op_sel_hi:[1,0]
	v_pk_fma_f32 v[32:33], v[32:33], v[144:145], v[164:165]
	v_pk_fma_f32 v[34:35], v[34:35], v[146:147], v[166:167]
	v_cvt_pk_f16_f32 v230, v32, v33
	v_cvt_pk_f16_f32 v231, v34, v35
	s_nop 1
	v_permlane16_swap_b32_e32 v228, v230
	v_permlane16_swap_b32_e32 v229, v231
	global_store_dwordx4 v177, v[228:231], s[80:81] offset:64
	v_add_u32_e32 v177, 0x8000, v177
	v_add_u32_e32 v178, 0x8000, v178
	global_load_dwordx4 v[192:195], v178, s[80:81]
	global_load_dwordx4 v[196:199], v178, s[80:81] offset:64
	s_waitcnt vmcnt(5)
	v_permlane16_swap_b32_e32 v184, v186
	v_permlane16_swap_b32_e32 v185, v187
	v_cvt_f32_f16_e32 v164, v184
	v_cvt_f32_f16_sdwa v165, v184 dst_sel:DWORD dst_unused:UNUSED_PAD src0_sel:WORD_1
	v_cvt_f32_f16_e32 v166, v185
	v_cvt_f32_f16_sdwa v167, v185 dst_sel:DWORD dst_unused:UNUSED_PAD src0_sel:WORD_1
	v_pk_mul_f32 v[164:165], v[164:165], s[84:85] op_sel_hi:[1,0]
	v_pk_mul_f32 v[166:167], v[166:167], s[84:85] op_sel_hi:[1,0]
	v_pk_fma_f32 v[36:37], v[36:37], v[132:133], v[164:165]
	v_pk_fma_f32 v[38:39], v[38:39], v[134:135], v[166:167]
	v_cvt_pk_f16_f32 v172, v36, v37
	v_cvt_pk_f16_f32 v173, v38, v39
	v_cvt_f32_f16_e32 v164, v186
	v_cvt_f32_f16_sdwa v165, v186 dst_sel:DWORD dst_unused:UNUSED_PAD src0_sel:WORD_1
	v_cvt_f32_f16_e32 v166, v187
	v_cvt_f32_f16_sdwa v167, v187 dst_sel:DWORD dst_unused:UNUSED_PAD src0_sel:WORD_1
	v_pk_mul_f32 v[164:165], v[164:165], s[84:85] op_sel_hi:[1,0]
	v_pk_mul_f32 v[166:167], v[166:167], s[84:85] op_sel_hi:[1,0]
	v_pk_fma_f32 v[40:41], v[40:41], v[136:137], v[164:165]
	v_pk_fma_f32 v[42:43], v[42:43], v[138:139], v[166:167]
	v_cvt_pk_f16_f32 v174, v40, v41
	v_cvt_pk_f16_f32 v175, v42, v43
	s_nop 1
	v_permlane16_swap_b32_e32 v172, v174
	v_permlane16_swap_b32_e32 v173, v175
	global_store_dwordx4 v177, v[172:175], s[80:81]
	s_waitcnt vmcnt(5)
	v_permlane16_swap_b32_e32 v188, v190
	v_permlane16_swap_b32_e32 v189, v191
	v_cvt_f32_f16_e32 v164, v188
	v_cvt_f32_f16_sdwa v165, v188 dst_sel:DWORD dst_unused:UNUSED_PAD src0_sel:WORD_1
	v_cvt_f32_f16_e32 v166, v189
	v_cvt_f32_f16_sdwa v167, v189 dst_sel:DWORD dst_unused:UNUSED_PAD src0_sel:WORD_1
	v_pk_mul_f32 v[164:165], v[164:165], s[84:85] op_sel_hi:[1,0]
	v_pk_mul_f32 v[166:167], v[166:167], s[84:85] op_sel_hi:[1,0]
	v_pk_fma_f32 v[44:45], v[44:45], v[140:141], v[164:165]
	v_pk_fma_f32 v[46:47], v[46:47], v[142:143], v[166:167]
	v_cvt_pk_f16_f32 v228, v44, v45
	v_cvt_pk_f16_f32 v229, v46, v47
	v_cvt_f32_f16_e32 v164, v190
	v_cvt_f32_f16_sdwa v165, v190 dst_sel:DWORD dst_unused:UNUSED_PAD src0_sel:WORD_1
	v_cvt_f32_f16_e32 v166, v191
	v_cvt_f32_f16_sdwa v167, v191 dst_sel:DWORD dst_unused:UNUSED_PAD src0_sel:WORD_1
	v_pk_mul_f32 v[164:165], v[164:165], s[84:85] op_sel_hi:[1,0]
	v_pk_mul_f32 v[166:167], v[166:167], s[84:85] op_sel_hi:[1,0]
	v_pk_fma_f32 v[48:49], v[48:49], v[144:145], v[164:165]
	v_pk_fma_f32 v[50:51], v[50:51], v[146:147], v[166:167]
	v_cvt_pk_f16_f32 v230, v48, v49
	v_cvt_pk_f16_f32 v231, v50, v51
	s_nop 1
	v_permlane16_swap_b32_e32 v228, v230
	v_permlane16_swap_b32_e32 v229, v231
	global_store_dwordx4 v177, v[228:231], s[80:81] offset:64
	v_add_u32_e32 v177, 0x8000, v177
	s_waitcnt vmcnt(3)
	v_permlane16_swap_b32_e32 v192, v194
	v_permlane16_swap_b32_e32 v193, v195
	v_cvt_f32_f16_e32 v164, v192
	v_cvt_f32_f16_sdwa v165, v192 dst_sel:DWORD dst_unused:UNUSED_PAD src0_sel:WORD_1
	v_cvt_f32_f16_e32 v166, v193
	v_cvt_f32_f16_sdwa v167, v193 dst_sel:DWORD dst_unused:UNUSED_PAD src0_sel:WORD_1
	v_pk_mul_f32 v[164:165], v[164:165], s[84:85] op_sel_hi:[1,0]
	v_pk_mul_f32 v[166:167], v[166:167], s[84:85] op_sel_hi:[1,0]
	v_pk_fma_f32 v[52:53], v[52:53], v[132:133], v[164:165]
	v_pk_fma_f32 v[54:55], v[54:55], v[134:135], v[166:167]
	v_cvt_pk_f16_f32 v172, v52, v53
	v_cvt_pk_f16_f32 v173, v54, v55
	v_cvt_f32_f16_e32 v164, v194
	v_cvt_f32_f16_sdwa v165, v194 dst_sel:DWORD dst_unused:UNUSED_PAD src0_sel:WORD_1
	v_cvt_f32_f16_e32 v166, v195
	v_cvt_f32_f16_sdwa v167, v195 dst_sel:DWORD dst_unused:UNUSED_PAD src0_sel:WORD_1
	v_pk_mul_f32 v[164:165], v[164:165], s[84:85] op_sel_hi:[1,0]
	v_pk_mul_f32 v[166:167], v[166:167], s[84:85] op_sel_hi:[1,0]
	v_pk_fma_f32 v[56:57], v[56:57], v[136:137], v[164:165]
	v_pk_fma_f32 v[58:59], v[58:59], v[138:139], v[166:167]
	v_cvt_pk_f16_f32 v174, v56, v57
	v_cvt_pk_f16_f32 v175, v58, v59
	s_nop 1
	v_permlane16_swap_b32_e32 v172, v174
	v_permlane16_swap_b32_e32 v173, v175
	global_store_dwordx4 v177, v[172:175], s[80:81]
	s_waitcnt vmcnt(3)
	v_permlane16_swap_b32_e32 v196, v198
	v_permlane16_swap_b32_e32 v197, v199
	v_cvt_f32_f16_e32 v164, v196
	v_cvt_f32_f16_sdwa v165, v196 dst_sel:DWORD dst_unused:UNUSED_PAD src0_sel:WORD_1
	v_cvt_f32_f16_e32 v166, v197
	v_cvt_f32_f16_sdwa v167, v197 dst_sel:DWORD dst_unused:UNUSED_PAD src0_sel:WORD_1
	v_pk_mul_f32 v[164:165], v[164:165], s[84:85] op_sel_hi:[1,0]
	v_pk_mul_f32 v[166:167], v[166:167], s[84:85] op_sel_hi:[1,0]
	v_pk_fma_f32 v[60:61], v[60:61], v[140:141], v[164:165]
	v_pk_fma_f32 v[62:63], v[62:63], v[142:143], v[166:167]
	v_cvt_pk_f16_f32 v228, v60, v61
	v_cvt_pk_f16_f32 v229, v62, v63
	v_cvt_f32_f16_e32 v164, v198
	v_cvt_f32_f16_sdwa v165, v198 dst_sel:DWORD dst_unused:UNUSED_PAD src0_sel:WORD_1
	v_cvt_f32_f16_e32 v166, v199
	v_cvt_f32_f16_sdwa v167, v199 dst_sel:DWORD dst_unused:UNUSED_PAD src0_sel:WORD_1
	v_pk_mul_f32 v[164:165], v[164:165], s[84:85] op_sel_hi:[1,0]
	v_pk_mul_f32 v[166:167], v[166:167], s[84:85] op_sel_hi:[1,0]
	v_pk_fma_f32 v[64:65], v[64:65], v[144:145], v[164:165]
	v_pk_fma_f32 v[66:67], v[66:67], v[146:147], v[166:167]
	v_cvt_pk_f16_f32 v230, v64, v65
	v_cvt_pk_f16_f32 v231, v66, v67
	s_nop 1
	v_permlane16_swap_b32_e32 v228, v230
	v_permlane16_swap_b32_e32 v229, v231
	global_store_dwordx4 v177, v[228:231], s[80:81] offset:64
	s_nop 1
	s_add_i32 s24, s24, s64
	s_cmpk_gt_i32 s24, 0x27f
	s_cbranch_scc1 .LBB0_759
	s_branch .LBB0_700
